# loop-edge edit on the five GEMM K-loops: back-edge bookkeeping in front of the closing barrier, next-tile pointer selects behind the first 8 ds_reads
# baseline (speedup 1.0000x reference)
; #define PG8_STAGE(bufoff, gbase, voff) do { _Pragma("unroll") for (int _i = 0; _i < 2; ++_i) \
;         __builtin_amdgcn_global_load_lds((const unsigned*)((const char*)(gbase) + (voff)[_i]), (PG8_LAS unsigned*)(lds + (bufoff) + ldsw + _i * 8192), 16, 0, 0); } while (0)
; #define PG8_LDA(dst, b, h) do { _Pragma("unroll") for (int m = 0; m < 4; ++m) _Pragma("unroll") for (int k = 0; k < 2; ++k) dst[m][k] = *(const PG8_LAS bf16x8*)(lds + PG8_SA(b, h) + aoff + m * 2048 + k * 1024); } while (0)
; #define PG8_LDB(dst, b, h) do { _Pragma("unroll") for (int n = 0; n < 2; ++n) _Pragma("unroll") for (int k = 0; k < 2; ++k) dst[n][k] = *(const PG8_LAS bf16x8*)(lds + PG8_SB(b, h) + boff + n * 2048 + k * 1024); } while (0)
; #define PG8_MMA(ai, bj, At, Bt) do { __builtin_amdgcn_s_setprio(1); _Pragma("unroll") for (int m = 0; m < 4; ++m) _Pragma("unroll") for (int n = 0; n < 2; ++n) _Pragma("unroll") for (int k = 0; k < 2; ++k) \
;         acc[ai][bj][m][n] = __builtin_amdgcn_mfma_f32_16x16x32_bf16(Bt[n][k], At[m][k], acc[ai][bj][m][n], 0, 0, 0); __builtin_amdgcn_s_setprio(0); } while (0)
; #define PG8_WAIT_V(n) asm volatile("s_waitcnt vmcnt(" #n ")" ::: "memory")
; #define PG8_BAR __builtin_amdgcn_s_barrier()
; template <class Epi, class Sched, bool ALIGN_EPI = false, bool SP2 = false>
; __device__ __forceinline__ void gemm_phase(PG8_LAS unsigned char* lds, const Gemm g, const Sched& S, const Epi& E, const int tid) {
;     ...
;         for (int t = 0; t < nt; t += 2) {
;             const bool last = (t == nt - 2);
;             const char* a1 = cA + (size_t)(t + 1) * kstep;
;             const char* a2 = last ? nA : cA + (size_t)(t + 2) * kstep; const char* b2 = last ? nB : cB + (size_t)(t + 2) * kstep;
;             const char* a3 = a2 + kstep; const char* b3 = b2 + kstep;
;             if (last && has_next) S.a_ready(nxt);
;             if constexpr (SP2) {
;             PG8_LDB(B0, 0, 0); PG8_LDB(B1, 0, 1); PG8_SCHED; PG8_LDA(At, 0, 0); PG8_STAGE(PG8_SA(1, 1), a1 + hstep, voffA);
;             PG8_WAIT_V(8); PG8_WAIT_L(0); PG8_BAR; PG8_MMA(0, 0, At, B0); PG8_MMA(0, 1, At, B1); PG8_BAR; PG8_SCHED;
;             PG8_LDA(At, 0, 1); PG8_STAGE(PG8_SB(0, 0), b2, voffB); PG8_STAGE(PG8_SB(0, 1), b2 + hstep, voffB); PG8_STAGE(PG8_SA(0, 0), a2, voffA);
;             PG8_WAIT_V(8); PG8_WAIT_L(0); PG8_BAR; PG8_MMA(1, 0, At, B0); PG8_MMA(1, 1, At, B1); PG8_BAR; PG8_SCHED;
.LBB0_99:
	s_add_i32 s50, 0, 0x10000
	s_add_i32 s52, 0, 0x14000
	v_add_u32_e32 v132, s50, v153
	v_add_u32_e32 v148, s52, v153
	ds_read_b128 v[116:119], v132
	ds_read_b128 v[120:123], v132 offset:1024
	ds_read_b128 v[124:127], v132 offset:2048
	ds_read_b128 v[132:135], v132 offset:3072
	ds_read_b128 v[178:181], v148
	ds_read_b128 v[182:185], v148 offset:1024
	ds_read_b128 v[186:189], v148 offset:2048
	ds_read_b128 v[190:193], v148 offset:3072
	s_add_u32 s20, s18, 0xfffc0080
	s_addc_u32 s21, s19, -1
	s_cmp_eq_u32 s49, 12
	s_cselect_b32 s23, s13, s21
	s_cselect_b32 s22, s45, s20
	s_cselect_b32 s21, s11, s48
	s_cselect_b32 s20, s46, s47
	v_lshl_add_u64 v[148:149], s[18:19], 0, v[172:173]
	s_add_i32 m0, s36, 0xc000
	ds_read_b128 v[194:197], v176
	ds_read_b128 v[198:201], v176 offset:1024
	ds_read_b128 v[202:205], v176 offset:2048
	ds_read_b128 v[206:209], v176 offset:3072
	ds_read_b128 v[210:213], v176 offset:4096
	ds_read_b128 v[214:217], v176 offset:5120
	ds_read_b128 v[218:221], v176 offset:6144
	ds_read_b128 v[222:225], v176 offset:7168
	global_load_lds_dwordx4 v[148:149], off
	v_lshl_add_u64 v[148:149], s[18:19], 0, v[174:175]
	s_add_i32 m0, s36, 0xe000
	s_nop 0
	global_load_lds_dwordx4 v[148:149], off
	s_waitcnt vmcnt(8)
	s_waitcnt lgkmcnt(0)
	s_barrier
	s_setprio 1
	s_waitcnt lgkmcnt(0)
	v_mfma_f32_16x16x32_bf16 v[144:147], v[116:119], v[194:197], v[144:147]
	v_mfma_f32_16x16x32_bf16 v[140:143], v[124:127], v[194:197], v[140:143]
	v_mfma_f32_16x16x32_bf16 v[112:115], v[116:119], v[202:205], v[112:115]
	v_mfma_f32_16x16x32_bf16 v[108:111], v[124:127], v[202:205], v[108:111]
	v_mfma_f32_16x16x32_bf16 v[96:99], v[116:119], v[210:213], v[96:99]
	v_mfma_f32_16x16x32_bf16 v[92:95], v[124:127], v[210:213], v[92:95]
	v_mfma_f32_16x16x32_bf16 v[80:83], v[116:119], v[218:221], v[80:83]
	v_mfma_f32_16x16x32_bf16 v[76:79], v[124:127], v[218:221], v[76:79]
	v_mfma_f32_16x16x32_bf16 v[144:147], v[120:123], v[198:201], v[144:147]
	v_mfma_f32_16x16x32_bf16 v[140:143], v[132:135], v[198:201], v[140:143]
	v_mfma_f32_16x16x32_bf16 v[112:115], v[120:123], v[206:209], v[112:115]
	v_mfma_f32_16x16x32_bf16 v[108:111], v[132:135], v[206:209], v[108:111]
	v_mfma_f32_16x16x32_bf16 v[96:99], v[120:123], v[214:217], v[96:99]
	v_mfma_f32_16x16x32_bf16 v[92:95], v[132:135], v[214:217], v[92:95]
	v_mfma_f32_16x16x32_bf16 v[80:83], v[120:123], v[222:225], v[80:83]
	v_mfma_f32_16x16x32_bf16 v[76:79], v[132:135], v[222:225], v[76:79]
	s_setprio 0
	s_setprio 1
	v_mfma_f32_16x16x32_bf16 v[136:139], v[178:181], v[194:197], v[136:139]
	v_mfma_f32_16x16x32_bf16 v[128:131], v[186:189], v[194:197], v[128:131]
	v_mfma_f32_16x16x32_bf16 v[104:107], v[178:181], v[202:205], v[104:107]
	v_mfma_f32_16x16x32_bf16 v[100:103], v[186:189], v[202:205], v[100:103]
	v_mfma_f32_16x16x32_bf16 v[88:91], v[178:181], v[210:213], v[88:91]
	v_mfma_f32_16x16x32_bf16 v[84:87], v[186:189], v[210:213], v[84:87]
	v_mfma_f32_16x16x32_bf16 v[72:75], v[178:181], v[218:221], v[72:75]
	v_mfma_f32_16x16x32_bf16 v[68:71], v[186:189], v[218:221], v[68:71]
	v_mfma_f32_16x16x32_bf16 v[136:139], v[182:185], v[198:201], v[136:139]
	v_mfma_f32_16x16x32_bf16 v[128:131], v[190:193], v[198:201], v[128:131]
	v_mfma_f32_16x16x32_bf16 v[104:107], v[182:185], v[206:209], v[104:107]
	v_mfma_f32_16x16x32_bf16 v[100:103], v[190:193], v[206:209], v[100:103]
	v_mfma_f32_16x16x32_bf16 v[88:91], v[182:185], v[214:217], v[88:91]
	v_mfma_f32_16x16x32_bf16 v[84:87], v[190:193], v[214:217], v[84:87]
	v_mfma_f32_16x16x32_bf16 v[72:75], v[182:185], v[222:225], v[72:75]
	v_mfma_f32_16x16x32_bf16 v[68:71], v[190:193], v[222:225], v[68:71]
	s_setprio 0
	s_barrier
	s_add_i32 s50, s50, s26
	v_lshl_add_u64 v[148:149], s[20:21], 0, v[168:169]
	s_mov_b32 m0, s50
	ds_read_b128 v[194:197], v176 offset:16384
	ds_read_b128 v[198:201], v176 offset:17408
	ds_read_b128 v[202:205], v176 offset:18432
	ds_read_b128 v[206:209], v176 offset:19456
	ds_read_b128 v[210:213], v176 offset:20480
	ds_read_b128 v[214:217], v176 offset:21504
	ds_read_b128 v[218:221], v176 offset:22528
	ds_read_b128 v[222:225], v176 offset:23552
	global_load_lds_dwordx4 v[148:149], off
	s_add_i32 m0, s50, 0x2000
	s_add_u32 s50, s20, 0x40000
	v_lshl_add_u64 v[150:151], s[20:21], 0, v[0:1]
	s_addc_u32 s51, s21, 0
	s_add_i32 s52, s52, s26
	global_load_lds_dwordx4 v[150:151], off
	v_lshl_add_u64 v[226:227], s[50:51], 0, v[168:169]
	s_mov_b32 m0, s52
	v_lshl_add_u64 v[238:239], s[22:23], 0, v[166:167]
	global_load_lds_dwordx4 v[226:227], off
	v_lshl_add_u64 v[226:227], s[50:51], 0, v[0:1]
	s_add_i32 m0, s52, 0x2000
	s_nop 0
	global_load_lds_dwordx4 v[226:227], off
	v_lshl_add_u64 v[226:227], s[22:23], 0, v[170:171]
	s_mov_b32 m0, s36
	s_nop 0
	global_load_lds_dwordx4 v[226:227], off
	s_mov_b32 m0, s37
	s_nop 0
	global_load_lds_dwordx4 v[238:239], off
	s_waitcnt vmcnt(8)
	s_waitcnt lgkmcnt(0)
	s_barrier
; #define PG8_STAGE(bufoff, gbase, voff) do { _Pragma("unroll") for (int _i = 0; _i < 2; ++_i) \
;         __builtin_amdgcn_global_load_lds((const unsigned*)((const char*)(gbase) + (voff)[_i]), (PG8_LAS unsigned*)(lds + (bufoff) + ldsw + _i * 8192), 16, 0, 0); } while (0)
; #define PG8_LDA(dst, b, h) do { _Pragma("unroll") for (int m = 0; m < 4; ++m) _Pragma("unroll") for (int k = 0; k < 2; ++k) dst[m][k] = *(const PG8_LAS bf16x8*)(lds + PG8_SA(b, h) + aoff + m * 2048 + k * 1024); } while (0)
; #define PG8_LDB(dst, b, h) do { _Pragma("unroll") for (int n = 0; n < 2; ++n) _Pragma("unroll") for (int k = 0; k < 2; ++k) dst[n][k] = *(const PG8_LAS bf16x8*)(lds + PG8_SB(b, h) + boff + n * 2048 + k * 1024); } while (0)
; #define PG8_MMA(ai, bj, At, Bt) do { __builtin_amdgcn_s_setprio(1); _Pragma("unroll") for (int m = 0; m < 4; ++m) _Pragma("unroll") for (int n = 0; n < 2; ++n) _Pragma("unroll") for (int k = 0; k < 2; ++k) \
;         acc[ai][bj][m][n] = __builtin_amdgcn_mfma_f32_16x16x32_bf16(Bt[n][k], At[m][k], acc[ai][bj][m][n], 0, 0, 0); __builtin_amdgcn_s_setprio(0); } while (0)
; #define PG8_WAIT_V(n) asm volatile("s_waitcnt vmcnt(" #n ")" ::: "memory")
; #define PG8_WAIT_L(n) asm volatile("s_waitcnt lgkmcnt(" #n ")" ::: "memory")
; #define PG8_BAR __builtin_amdgcn_s_barrier()
; #define PG8_SCHED __builtin_amdgcn_sched_barrier(0)
; template <class Epi, class Sched, bool ALIGN_EPI = false, bool SP2 = false>
; __device__ __forceinline__ void gemm_phase(PG8_LAS unsigned char* lds, const Gemm g, const Sched& S, const Epi& E, const int tid) {
;     ...
;             PG8_WAIT_V(8); PG8_WAIT_L(0); PG8_BAR; PG8_MMA(1, 0, At, B0); PG8_MMA(1, 1, At, B1); PG8_BAR; PG8_SCHED;
;             PG8_LDB(B0, 1, 0); PG8_LDB(B1, 1, 1); PG8_SCHED; PG8_LDA(At, 1, 0); PG8_STAGE(PG8_SA(0, 1), a2 + hstep, voffA);
;             PG8_WAIT_V(8); PG8_WAIT_L(0); PG8_BAR; PG8_MMA(0, 0, At, B0); PG8_MMA(0, 1, At, B1); PG8_BAR; PG8_SCHED;
	s_setprio 1
	s_waitcnt lgkmcnt(0)
	v_mfma_f32_16x16x32_bf16 v[64:67], v[116:119], v[194:197], v[64:67]
	v_mfma_f32_16x16x32_bf16 v[60:63], v[124:127], v[194:197], v[60:63]
	v_mfma_f32_16x16x32_bf16 v[56:59], v[116:119], v[202:205], v[56:59]
	v_mfma_f32_16x16x32_bf16 v[48:51], v[124:127], v[202:205], v[48:51]
	v_mfma_f32_16x16x32_bf16 v[40:43], v[116:119], v[210:213], v[40:43]
	v_mfma_f32_16x16x32_bf16 v[32:35], v[124:127], v[210:213], v[32:35]
	v_mfma_f32_16x16x32_bf16 v[24:27], v[116:119], v[218:221], v[24:27]
	v_mfma_f32_16x16x32_bf16 v[16:19], v[124:127], v[218:221], v[16:19]
	v_mfma_f32_16x16x32_bf16 v[64:67], v[120:123], v[198:201], v[64:67]
	v_mfma_f32_16x16x32_bf16 v[60:63], v[132:135], v[198:201], v[60:63]
	v_mfma_f32_16x16x32_bf16 v[56:59], v[120:123], v[206:209], v[56:59]
	v_mfma_f32_16x16x32_bf16 v[48:51], v[132:135], v[206:209], v[48:51]
	v_mfma_f32_16x16x32_bf16 v[40:43], v[120:123], v[214:217], v[40:43]
	v_mfma_f32_16x16x32_bf16 v[32:35], v[132:135], v[214:217], v[32:35]
	v_mfma_f32_16x16x32_bf16 v[24:27], v[120:123], v[222:225], v[24:27]
	v_mfma_f32_16x16x32_bf16 v[16:19], v[132:135], v[222:225], v[16:19]
	s_setprio 0
	s_setprio 1
	v_mfma_f32_16x16x32_bf16 v[52:55], v[178:181], v[194:197], v[52:55]
	v_mfma_f32_16x16x32_bf16 v[44:47], v[186:189], v[194:197], v[44:47]
	v_mfma_f32_16x16x32_bf16 v[36:39], v[178:181], v[202:205], v[36:39]
	v_mfma_f32_16x16x32_bf16 v[28:31], v[186:189], v[202:205], v[28:31]
	v_mfma_f32_16x16x32_bf16 v[20:23], v[178:181], v[210:213], v[20:23]
	v_mfma_f32_16x16x32_bf16 v[12:15], v[186:189], v[210:213], v[12:15]
	v_mfma_f32_16x16x32_bf16 v[8:11], v[178:181], v[218:221], v[8:11]
	v_mfma_f32_16x16x32_bf16 v[4:7], v[186:189], v[218:221], v[4:7]
	v_mfma_f32_16x16x32_bf16 v[52:55], v[182:185], v[198:201], v[52:55]
	v_mfma_f32_16x16x32_bf16 v[44:47], v[190:193], v[198:201], v[44:47]
	v_mfma_f32_16x16x32_bf16 v[36:39], v[182:185], v[206:209], v[36:39]
	v_mfma_f32_16x16x32_bf16 v[28:31], v[190:193], v[206:209], v[28:31]
	v_mfma_f32_16x16x32_bf16 v[20:23], v[182:185], v[214:217], v[20:23]
	v_mfma_f32_16x16x32_bf16 v[12:15], v[190:193], v[214:217], v[12:15]
	v_mfma_f32_16x16x32_bf16 v[8:11], v[182:185], v[222:225], v[8:11]
	v_mfma_f32_16x16x32_bf16 v[4:7], v[190:193], v[222:225], v[4:7]
	s_setprio 0
	s_barrier
	s_add_i32 s50, 0, 0x18000
	s_add_i32 s51, 0, 0x1c000
	v_add_u32_e32 v132, s50, v153
	v_add_u32_e32 v177, s51, v153
	ds_read_b128 v[116:119], v132
	ds_read_b128 v[120:123], v132 offset:1024
	ds_read_b128 v[124:127], v132 offset:2048
	ds_read_b128 v[132:135], v132 offset:3072
	ds_read_b128 v[178:181], v177
	ds_read_b128 v[182:185], v177 offset:1024
	ds_read_b128 v[186:189], v177 offset:2048
	ds_read_b128 v[190:193], v177 offset:3072
	s_add_u32 s22, s22, 0x40000
	s_addc_u32 s23, s23, 0
	s_mov_b32 m0, s38
	v_lshl_add_u64 v[240:241], s[22:23], 0, v[170:171]
	ds_read_b128 v[194:197], v176 offset:32768
	ds_read_b128 v[198:201], v176 offset:33792
	ds_read_b128 v[202:205], v176 offset:34816
	ds_read_b128 v[206:209], v176 offset:35840
	ds_read_b128 v[210:213], v176 offset:36864
	ds_read_b128 v[214:217], v176 offset:37888
	ds_read_b128 v[218:221], v176 offset:38912
	ds_read_b128 v[222:225], v176 offset:39936
	global_load_lds_dwordx4 v[240:241], off
	v_lshl_add_u64 v[240:241], s[22:23], 0, v[166:167]
	s_mov_b32 m0, s39
	s_nop 0
	global_load_lds_dwordx4 v[240:241], off
	s_waitcnt vmcnt(8)
	s_waitcnt lgkmcnt(0)
	s_barrier
	s_setprio 1
	s_waitcnt lgkmcnt(0)
	v_mfma_f32_16x16x32_bf16 v[144:147], v[116:119], v[194:197], v[144:147]
	v_mfma_f32_16x16x32_bf16 v[140:143], v[124:127], v[194:197], v[140:143]
	v_mfma_f32_16x16x32_bf16 v[112:115], v[116:119], v[202:205], v[112:115]
	v_mfma_f32_16x16x32_bf16 v[108:111], v[124:127], v[202:205], v[108:111]
	v_mfma_f32_16x16x32_bf16 v[96:99], v[116:119], v[210:213], v[96:99]
	v_mfma_f32_16x16x32_bf16 v[92:95], v[124:127], v[210:213], v[92:95]
	v_mfma_f32_16x16x32_bf16 v[80:83], v[116:119], v[218:221], v[80:83]
	v_mfma_f32_16x16x32_bf16 v[76:79], v[124:127], v[218:221], v[76:79]
	v_mfma_f32_16x16x32_bf16 v[144:147], v[120:123], v[198:201], v[144:147]
	v_mfma_f32_16x16x32_bf16 v[140:143], v[132:135], v[198:201], v[140:143]
	v_mfma_f32_16x16x32_bf16 v[112:115], v[120:123], v[206:209], v[112:115]
	v_mfma_f32_16x16x32_bf16 v[108:111], v[132:135], v[206:209], v[108:111]
	v_mfma_f32_16x16x32_bf16 v[96:99], v[120:123], v[214:217], v[96:99]
	v_mfma_f32_16x16x32_bf16 v[92:95], v[132:135], v[214:217], v[92:95]
	v_mfma_f32_16x16x32_bf16 v[80:83], v[120:123], v[222:225], v[80:83]
	v_mfma_f32_16x16x32_bf16 v[76:79], v[132:135], v[222:225], v[76:79]
	s_setprio 0
	s_setprio 1
	v_mfma_f32_16x16x32_bf16 v[136:139], v[178:181], v[194:197], v[136:139]
	v_mfma_f32_16x16x32_bf16 v[128:131], v[186:189], v[194:197], v[128:131]
	v_mfma_f32_16x16x32_bf16 v[104:107], v[178:181], v[202:205], v[104:107]
	v_mfma_f32_16x16x32_bf16 v[100:103], v[186:189], v[202:205], v[100:103]
	v_mfma_f32_16x16x32_bf16 v[88:91], v[178:181], v[210:213], v[88:91]
	v_mfma_f32_16x16x32_bf16 v[84:87], v[186:189], v[210:213], v[84:87]
	v_mfma_f32_16x16x32_bf16 v[72:75], v[178:181], v[218:221], v[72:75]
	v_mfma_f32_16x16x32_bf16 v[68:71], v[186:189], v[218:221], v[68:71]
	v_mfma_f32_16x16x32_bf16 v[136:139], v[182:185], v[198:201], v[136:139]
	v_mfma_f32_16x16x32_bf16 v[128:131], v[190:193], v[198:201], v[128:131]
	v_mfma_f32_16x16x32_bf16 v[104:107], v[182:185], v[206:209], v[104:107]
	v_mfma_f32_16x16x32_bf16 v[100:103], v[190:193], v[206:209], v[100:103]
	v_mfma_f32_16x16x32_bf16 v[88:91], v[182:185], v[214:217], v[88:91]
	v_mfma_f32_16x16x32_bf16 v[84:87], v[190:193], v[214:217], v[84:87]
	v_mfma_f32_16x16x32_bf16 v[72:75], v[182:185], v[222:225], v[72:75]
	v_mfma_f32_16x16x32_bf16 v[68:71], v[190:193], v[222:225], v[68:71]
	s_setprio 0
	s_barrier
; #define PG8_STAGE(bufoff, gbase, voff) do { _Pragma("unroll") for (int _i = 0; _i < 2; ++_i) \
;         __builtin_amdgcn_global_load_lds((const unsigned*)((const char*)(gbase) + (voff)[_i]), (PG8_LAS unsigned*)(lds + (bufoff) + ldsw + _i * 8192), 16, 0, 0); } while (0)
; #define PG8_LDA(dst, b, h) do { _Pragma("unroll") for (int m = 0; m < 4; ++m) _Pragma("unroll") for (int k = 0; k < 2; ++k) dst[m][k] = *(const PG8_LAS bf16x8*)(lds + PG8_SA(b, h) + aoff + m * 2048 + k * 1024); } while (0)
; #define PG8_MMA(ai, bj, At, Bt) do { __builtin_amdgcn_s_setprio(1); _Pragma("unroll") for (int m = 0; m < 4; ++m) _Pragma("unroll") for (int n = 0; n < 2; ++n) _Pragma("unroll") for (int k = 0; k < 2; ++k) \
;         acc[ai][bj][m][n] = __builtin_amdgcn_mfma_f32_16x16x32_bf16(Bt[n][k], At[m][k], acc[ai][bj][m][n], 0, 0, 0); __builtin_amdgcn_s_setprio(0); } while (0)
; #define PG8_WAIT_V(n) asm volatile("s_waitcnt vmcnt(" #n ")" ::: "memory")
; #define PG8_WAIT_L(n) asm volatile("s_waitcnt lgkmcnt(" #n ")" ::: "memory")
; #define PG8_BAR __builtin_amdgcn_s_barrier()
; #define PG8_SCHED __builtin_amdgcn_sched_barrier(0)
; template <class Epi, class Sched, bool ALIGN_EPI = false, bool SP2 = false>
; __device__ __forceinline__ void gemm_phase(PG8_LAS unsigned char* lds, const Gemm g, const Sched& S, const Epi& E, const int tid) {
;     ...
;         for (int t = 0; t < nt; t += 2) {
;     ...
;             PG8_WAIT_V(8); PG8_WAIT_L(0); PG8_BAR; PG8_MMA(0, 0, At, B0); PG8_MMA(0, 1, At, B1); PG8_BAR; PG8_SCHED;
;             PG8_LDA(At, 1, 1); PG8_STAGE(PG8_SB(1, 0), b3, voffB); PG8_STAGE(PG8_SB(1, 1), b3 + hstep, voffB); PG8_STAGE(PG8_SA(1, 0), a3, voffA);
;             PG8_WAIT_V(8); PG8_WAIT_L(0); PG8_BAR; PG8_MMA(1, 0, At, B0); PG8_MMA(1, 1, At, B1); PG8_BAR; PG8_SCHED;
	s_add_i32 s22, s50, s26
	v_lshl_add_u64 v[148:149], v[148:149], 0, s[0:1]
	s_mov_b32 m0, s22
	ds_read_b128 v[194:197], v176 offset:49152
	ds_read_b128 v[198:201], v176 offset:50176
	ds_read_b128 v[202:205], v176 offset:51200
	ds_read_b128 v[206:209], v176 offset:52224
	ds_read_b128 v[210:213], v176 offset:53248
	ds_read_b128 v[214:217], v176 offset:54272
	ds_read_b128 v[218:221], v176 offset:55296
	ds_read_b128 v[222:225], v176 offset:56320
	global_load_lds_dwordx4 v[148:149], off
	s_add_i32 m0, s22, 0x2000
	s_add_u32 s20, s20, 0x40080
	v_lshl_add_u64 v[148:149], v[150:151], 0, s[0:1]
	s_addc_u32 s21, s21, 0
	s_add_i32 s22, s51, s26
	global_load_lds_dwordx4 v[148:149], off
	v_lshl_add_u64 v[148:149], s[20:21], 0, v[168:169]
	s_mov_b32 m0, s22
	s_nop 0
	global_load_lds_dwordx4 v[148:149], off
	v_lshl_add_u64 v[148:149], s[20:21], 0, v[0:1]
	s_add_i32 m0, s22, 0x2000
	s_nop 0
	global_load_lds_dwordx4 v[148:149], off
	v_lshl_add_u64 v[148:149], v[226:227], 0, s[0:1]
	s_mov_b32 m0, s40
	s_nop 0
	global_load_lds_dwordx4 v[148:149], off
	v_lshl_add_u64 v[148:149], v[238:239], 0, s[0:1]
	s_mov_b32 m0, s41
	s_nop 0
	global_load_lds_dwordx4 v[148:149], off
	s_waitcnt vmcnt(8)
	s_waitcnt lgkmcnt(0)
	s_barrier
	s_setprio 1
	s_waitcnt lgkmcnt(0)
	v_mfma_f32_16x16x32_bf16 v[64:67], v[116:119], v[194:197], v[64:67]
	v_mfma_f32_16x16x32_bf16 v[60:63], v[124:127], v[194:197], v[60:63]
	v_mfma_f32_16x16x32_bf16 v[56:59], v[116:119], v[202:205], v[56:59]
	v_mfma_f32_16x16x32_bf16 v[48:51], v[124:127], v[202:205], v[48:51]
	v_mfma_f32_16x16x32_bf16 v[40:43], v[116:119], v[210:213], v[40:43]
	v_mfma_f32_16x16x32_bf16 v[32:35], v[124:127], v[210:213], v[32:35]
	v_mfma_f32_16x16x32_bf16 v[24:27], v[116:119], v[218:221], v[24:27]
	v_mfma_f32_16x16x32_bf16 v[16:19], v[124:127], v[218:221], v[16:19]
	v_mfma_f32_16x16x32_bf16 v[64:67], v[120:123], v[198:201], v[64:67]
	v_mfma_f32_16x16x32_bf16 v[60:63], v[132:135], v[198:201], v[60:63]
	v_mfma_f32_16x16x32_bf16 v[56:59], v[120:123], v[206:209], v[56:59]
	v_mfma_f32_16x16x32_bf16 v[48:51], v[132:135], v[206:209], v[48:51]
	v_mfma_f32_16x16x32_bf16 v[40:43], v[120:123], v[214:217], v[40:43]
	v_mfma_f32_16x16x32_bf16 v[32:35], v[132:135], v[214:217], v[32:35]
	v_mfma_f32_16x16x32_bf16 v[24:27], v[120:123], v[222:225], v[24:27]
	v_mfma_f32_16x16x32_bf16 v[16:19], v[132:135], v[222:225], v[16:19]
	s_setprio 0
	s_setprio 1
	v_mfma_f32_16x16x32_bf16 v[52:55], v[178:181], v[194:197], v[52:55]
	v_mfma_f32_16x16x32_bf16 v[44:47], v[186:189], v[194:197], v[44:47]
	v_mfma_f32_16x16x32_bf16 v[36:39], v[178:181], v[202:205], v[36:39]
	v_mfma_f32_16x16x32_bf16 v[28:31], v[186:189], v[202:205], v[28:31]
	v_mfma_f32_16x16x32_bf16 v[20:23], v[178:181], v[210:213], v[20:23]
	v_mfma_f32_16x16x32_bf16 v[12:15], v[186:189], v[210:213], v[12:15]
	v_mfma_f32_16x16x32_bf16 v[8:11], v[178:181], v[218:221], v[8:11]
	v_mfma_f32_16x16x32_bf16 v[4:7], v[186:189], v[218:221], v[4:7]
	v_mfma_f32_16x16x32_bf16 v[52:55], v[182:185], v[198:201], v[52:55]
	v_mfma_f32_16x16x32_bf16 v[44:47], v[190:193], v[198:201], v[44:47]
	v_mfma_f32_16x16x32_bf16 v[36:39], v[182:185], v[206:209], v[36:39]
	v_mfma_f32_16x16x32_bf16 v[28:31], v[190:193], v[206:209], v[28:31]
	v_mfma_f32_16x16x32_bf16 v[20:23], v[182:185], v[214:217], v[20:23]
	v_mfma_f32_16x16x32_bf16 v[12:15], v[190:193], v[214:217], v[12:15]
	v_mfma_f32_16x16x32_bf16 v[8:11], v[182:185], v[222:225], v[8:11]
	v_mfma_f32_16x16x32_bf16 v[4:7], v[190:193], v[222:225], v[4:7]
	s_setprio 0
	s_add_i32 s49, s49, 2
	s_add_u32 s18, s18, 0x100
	s_addc_u32 s19, s19, 0
	s_add_u32 s47, s47, 0x100
	s_addc_u32 s48, s48, 0
	s_cmp_gt_u32 s49, 13
	s_barrier
	s_cbranch_scc0 .LBB0_99
	s_and_b64 vcc, exec, s[8:9]
	s_cbranch_vccz .LBB0_102
	s_barrier

; #define PG8_STAGE(bufoff, gbase, voff) do { _Pragma("unroll") for (int _i = 0; _i < 2; ++_i) \
;         __builtin_amdgcn_global_load_lds((const unsigned*)((const char*)(gbase) + (voff)[_i]), (PG8_LAS unsigned*)(lds + (bufoff) + ldsw + _i * 8192), 16, 0, 0); } while (0)
; #define PG8_LDA(dst, b, h) do { _Pragma("unroll") for (int m = 0; m < 4; ++m) _Pragma("unroll") for (int k = 0; k < 2; ++k) dst[m][k] = *(const PG8_LAS bf16x8*)(lds + PG8_SA(b, h) + aoff + m * 2048 + k * 1024); } while (0)
; #define PG8_LDB(dst, b, h) do { _Pragma("unroll") for (int n = 0; n < 2; ++n) _Pragma("unroll") for (int k = 0; k < 2; ++k) dst[n][k] = *(const PG8_LAS bf16x8*)(lds + PG8_SB(b, h) + boff + n * 2048 + k * 1024); } while (0)
; #define PG8_MMA(ai, bj, At, Bt) do { __builtin_amdgcn_s_setprio(1); _Pragma("unroll") for (int m = 0; m < 4; ++m) _Pragma("unroll") for (int n = 0; n < 2; ++n) _Pragma("unroll") for (int k = 0; k < 2; ++k) \
;         acc[ai][bj][m][n] = __builtin_amdgcn_mfma_f32_16x16x32_bf16(Bt[n][k], At[m][k], acc[ai][bj][m][n], 0, 0, 0); __builtin_amdgcn_s_setprio(0); } while (0)
; #define PG8_WAIT_V(n) asm volatile("s_waitcnt vmcnt(" #n ")" ::: "memory")
; #define PG8_BAR __builtin_amdgcn_s_barrier()
; template <class Epi, class Sched, bool ALIGN_EPI = false, bool SP2 = false>
; __device__ __forceinline__ void gemm_phase(PG8_LAS unsigned char* lds, const Gemm g, const Sched& S, const Epi& E, const int tid) {
;     ...
;         for (int t = 0; t < nt; t += 2) {
;             const bool last = (t == nt - 2);
;             const char* a1 = cA + (size_t)(t + 1) * kstep;
;             const char* a2 = last ? nA : cA + (size_t)(t + 2) * kstep; const char* b2 = last ? nB : cB + (size_t)(t + 2) * kstep;
;             const char* a3 = a2 + kstep; const char* b3 = b2 + kstep;
;             if (last && has_next) S.a_ready(nxt);
;             if constexpr (SP2) {
;             PG8_LDB(B0, 0, 0); PG8_LDB(B1, 0, 1); PG8_SCHED; PG8_LDA(At, 0, 0); PG8_STAGE(PG8_SA(1, 1), a1 + hstep, voffA);
;             PG8_WAIT_V(8); PG8_WAIT_L(0); PG8_BAR; PG8_MMA(0, 0, At, B0); PG8_MMA(0, 1, At, B1); PG8_BAR; PG8_SCHED;
;             PG8_LDA(At, 0, 1); PG8_STAGE(PG8_SB(0, 0), b2, voffB); PG8_STAGE(PG8_SB(0, 1), b2 + hstep, voffB); PG8_STAGE(PG8_SA(0, 0), a2, voffA);
;             PG8_WAIT_V(8); PG8_WAIT_L(0); PG8_BAR; PG8_MMA(1, 0, At, B0); PG8_MMA(1, 1, At, B1); PG8_BAR; PG8_SCHED;
.LBB0_293:
	s_add_i32 s55, 0, 0x10000
	v_add_u32_e32 v146, s55, v165
	s_add_i32 s58, 0, 0x14000
	ds_read_b128 v[166:169], v146
	ds_read_b128 v[172:175], v146 offset:1024
	ds_read_b128 v[176:179], v146 offset:2048
	ds_read_b128 v[180:183], v146 offset:3072
	v_add_u32_e32 v146, s58, v165
	ds_read_b128 v[184:187], v146
	ds_read_b128 v[188:191], v146 offset:1024
	ds_read_b128 v[192:195], v146 offset:2048
	ds_read_b128 v[196:199], v146 offset:3072
	s_add_u32 s26, s2, 0xfffc0080
	s_addc_u32 s27, s3, -1
	s_cmp_eq_u32 s54, 12
	s_cselect_b32 s37, s17, s27
	s_cselect_b32 s36, s23, s26
	s_cselect_b32 s27, s15, s53
	s_cselect_b32 s26, s51, s52
	v_lshl_add_u64 v[146:147], s[2:3], 0, v[142:143]
	s_add_i32 m0, s25, 0xc000
	ds_read_b128 v[200:203], v171
	ds_read_b128 v[204:207], v171 offset:1024
	ds_read_b128 v[208:211], v171 offset:2048
	ds_read_b128 v[212:215], v171 offset:3072
	ds_read_b128 v[216:219], v171 offset:4096
	ds_read_b128 v[220:223], v171 offset:5120
	ds_read_b128 v[224:227], v171 offset:6144
	ds_read_b128 v[238:241], v171 offset:7168
	global_load_lds_dwordx4 v[146:147], off
	v_lshl_add_u64 v[146:147], s[2:3], 0, v[144:145]
	s_add_i32 m0, s25, 0xe000
	s_nop 0
	global_load_lds_dwordx4 v[146:147], off
	s_waitcnt vmcnt(8)
	s_waitcnt lgkmcnt(0)
	s_barrier
	s_setprio 1
	s_waitcnt lgkmcnt(0)
	v_mfma_f32_16x16x32_bf16 v[72:75], v[166:169], v[200:203], v[72:75]
	v_mfma_f32_16x16x32_bf16 v[68:71], v[176:179], v[200:203], v[68:71]
	v_mfma_f32_16x16x32_bf16 v[64:67], v[166:169], v[208:211], v[64:67]
	v_mfma_f32_16x16x32_bf16 v[60:63], v[176:179], v[208:211], v[60:63]
	v_mfma_f32_16x16x32_bf16 v[56:59], v[166:169], v[216:219], v[56:59]
	v_mfma_f32_16x16x32_bf16 v[52:55], v[176:179], v[216:219], v[52:55]
	v_mfma_f32_16x16x32_bf16 v[48:51], v[166:169], v[224:227], v[48:51]
	v_mfma_f32_16x16x32_bf16 v[44:47], v[176:179], v[224:227], v[44:47]
	v_mfma_f32_16x16x32_bf16 v[72:75], v[172:175], v[204:207], v[72:75]
	v_mfma_f32_16x16x32_bf16 v[68:71], v[180:183], v[204:207], v[68:71]
	v_mfma_f32_16x16x32_bf16 v[64:67], v[172:175], v[212:215], v[64:67]
	v_mfma_f32_16x16x32_bf16 v[60:63], v[180:183], v[212:215], v[60:63]
	v_mfma_f32_16x16x32_bf16 v[56:59], v[172:175], v[220:223], v[56:59]
	v_mfma_f32_16x16x32_bf16 v[52:55], v[180:183], v[220:223], v[52:55]
	v_mfma_f32_16x16x32_bf16 v[48:51], v[172:175], v[238:241], v[48:51]
	v_mfma_f32_16x16x32_bf16 v[44:47], v[180:183], v[238:241], v[44:47]
	s_setprio 0
	s_setprio 1
	v_mfma_f32_16x16x32_bf16 v[128:131], v[184:187], v[200:203], v[128:131]
	v_mfma_f32_16x16x32_bf16 v[124:127], v[192:195], v[200:203], v[124:127]
	v_mfma_f32_16x16x32_bf16 v[120:123], v[184:187], v[208:211], v[120:123]
	v_mfma_f32_16x16x32_bf16 v[116:119], v[192:195], v[208:211], v[116:119]
	v_mfma_f32_16x16x32_bf16 v[112:115], v[184:187], v[216:219], v[112:115]
	v_mfma_f32_16x16x32_bf16 v[108:111], v[192:195], v[216:219], v[108:111]
	v_mfma_f32_16x16x32_bf16 v[104:107], v[184:187], v[224:227], v[104:107]
	v_mfma_f32_16x16x32_bf16 v[100:103], v[192:195], v[224:227], v[100:103]
	v_mfma_f32_16x16x32_bf16 v[128:131], v[188:191], v[204:207], v[128:131]
	v_mfma_f32_16x16x32_bf16 v[124:127], v[196:199], v[204:207], v[124:127]
	v_mfma_f32_16x16x32_bf16 v[120:123], v[188:191], v[212:215], v[120:123]
	v_mfma_f32_16x16x32_bf16 v[116:119], v[196:199], v[212:215], v[116:119]
	v_mfma_f32_16x16x32_bf16 v[112:115], v[188:191], v[220:223], v[112:115]
	v_mfma_f32_16x16x32_bf16 v[108:111], v[196:199], v[220:223], v[108:111]
	v_mfma_f32_16x16x32_bf16 v[104:107], v[188:191], v[238:241], v[104:107]
	v_mfma_f32_16x16x32_bf16 v[100:103], v[196:199], v[238:241], v[100:103]
	s_setprio 0
	s_barrier
	s_add_i32 s55, s55, s43
	v_lshl_add_u64 v[146:147], s[26:27], 0, v[132:133]
	s_mov_b32 m0, s55
	ds_read_b128 v[200:203], v171 offset:16384
	ds_read_b128 v[204:207], v171 offset:17408
	ds_read_b128 v[208:211], v171 offset:18432
	ds_read_b128 v[212:215], v171 offset:19456
	ds_read_b128 v[216:219], v171 offset:20480
	ds_read_b128 v[220:223], v171 offset:21504
	ds_read_b128 v[224:227], v171 offset:22528
	ds_read_b128 v[238:241], v171 offset:23552
	global_load_lds_dwordx4 v[146:147], off
	s_add_i32 m0, s55, 0x2000
	s_add_u32 s56, s26, 0x40000
	v_lshl_add_u64 v[148:149], s[26:27], 0, v[136:137]
	s_addc_u32 s57, s27, 0
	s_add_i32 s55, s58, s43
	global_load_lds_dwordx4 v[148:149], off
	v_lshl_add_u64 v[150:151], s[56:57], 0, v[132:133]
	s_mov_b32 m0, s55
	v_lshl_add_u64 v[242:243], s[36:37], 0, v[134:135]
	global_load_lds_dwordx4 v[150:151], off
	v_lshl_add_u64 v[150:151], s[56:57], 0, v[136:137]
	s_add_i32 m0, s55, 0x2000
	s_nop 0
	global_load_lds_dwordx4 v[150:151], off
	v_lshl_add_u64 v[150:151], s[36:37], 0, v[0:1]
	s_mov_b32 m0, s25
	s_nop 0
	global_load_lds_dwordx4 v[150:151], off
	s_mov_b32 m0, s44
	s_nop 0
	global_load_lds_dwordx4 v[242:243], off
	s_waitcnt vmcnt(8)
	s_waitcnt lgkmcnt(0)
	s_barrier
; #define PG8_STAGE(bufoff, gbase, voff) do { _Pragma("unroll") for (int _i = 0; _i < 2; ++_i) \
;         __builtin_amdgcn_global_load_lds((const unsigned*)((const char*)(gbase) + (voff)[_i]), (PG8_LAS unsigned*)(lds + (bufoff) + ldsw + _i * 8192), 16, 0, 0); } while (0)
; #define PG8_LDA(dst, b, h) do { _Pragma("unroll") for (int m = 0; m < 4; ++m) _Pragma("unroll") for (int k = 0; k < 2; ++k) dst[m][k] = *(const PG8_LAS bf16x8*)(lds + PG8_SA(b, h) + aoff + m * 2048 + k * 1024); } while (0)
; #define PG8_LDB(dst, b, h) do { _Pragma("unroll") for (int n = 0; n < 2; ++n) _Pragma("unroll") for (int k = 0; k < 2; ++k) dst[n][k] = *(const PG8_LAS bf16x8*)(lds + PG8_SB(b, h) + boff + n * 2048 + k * 1024); } while (0)
; #define PG8_MMA(ai, bj, At, Bt) do { __builtin_amdgcn_s_setprio(1); _Pragma("unroll") for (int m = 0; m < 4; ++m) _Pragma("unroll") for (int n = 0; n < 2; ++n) _Pragma("unroll") for (int k = 0; k < 2; ++k) \
;         acc[ai][bj][m][n] = __builtin_amdgcn_mfma_f32_16x16x32_bf16(Bt[n][k], At[m][k], acc[ai][bj][m][n], 0, 0, 0); __builtin_amdgcn_s_setprio(0); } while (0)
; #define PG8_WAIT_V(n) asm volatile("s_waitcnt vmcnt(" #n ")" ::: "memory")
; #define PG8_WAIT_L(n) asm volatile("s_waitcnt lgkmcnt(" #n ")" ::: "memory")
; #define PG8_BAR __builtin_amdgcn_s_barrier()
; #define PG8_SCHED __builtin_amdgcn_sched_barrier(0)
; template <class Epi, class Sched, bool ALIGN_EPI = false, bool SP2 = false>
; __device__ __forceinline__ void gemm_phase(PG8_LAS unsigned char* lds, const Gemm g, const Sched& S, const Epi& E, const int tid) {
;     ...
;             PG8_WAIT_V(8); PG8_WAIT_L(0); PG8_BAR; PG8_MMA(1, 0, At, B0); PG8_MMA(1, 1, At, B1); PG8_BAR; PG8_SCHED;
;             PG8_LDB(B0, 1, 0); PG8_LDB(B1, 1, 1); PG8_SCHED; PG8_LDA(At, 1, 0); PG8_STAGE(PG8_SA(0, 1), a2 + hstep, voffA);
;             PG8_WAIT_V(8); PG8_WAIT_L(0); PG8_BAR; PG8_MMA(0, 0, At, B0); PG8_MMA(0, 1, At, B1); PG8_BAR; PG8_SCHED;
	s_setprio 1
	s_waitcnt lgkmcnt(0)
	v_mfma_f32_16x16x32_bf16 v[40:43], v[166:169], v[200:203], v[40:43]
	v_mfma_f32_16x16x32_bf16 v[36:39], v[176:179], v[200:203], v[36:39]
	v_mfma_f32_16x16x32_bf16 v[32:35], v[166:169], v[208:211], v[32:35]
	v_mfma_f32_16x16x32_bf16 v[28:31], v[176:179], v[208:211], v[28:31]
	v_mfma_f32_16x16x32_bf16 v[24:27], v[166:169], v[216:219], v[24:27]
	v_mfma_f32_16x16x32_bf16 v[20:23], v[176:179], v[216:219], v[20:23]
	v_mfma_f32_16x16x32_bf16 v[8:11], v[166:169], v[224:227], v[8:11]
	v_mfma_f32_16x16x32_bf16 v[4:7], v[176:179], v[224:227], v[4:7]
	v_mfma_f32_16x16x32_bf16 v[40:43], v[172:175], v[204:207], v[40:43]
	v_mfma_f32_16x16x32_bf16 v[36:39], v[180:183], v[204:207], v[36:39]
	v_mfma_f32_16x16x32_bf16 v[32:35], v[172:175], v[212:215], v[32:35]
	v_mfma_f32_16x16x32_bf16 v[28:31], v[180:183], v[212:215], v[28:31]
	v_mfma_f32_16x16x32_bf16 v[24:27], v[172:175], v[220:223], v[24:27]
	v_mfma_f32_16x16x32_bf16 v[20:23], v[180:183], v[220:223], v[20:23]
	v_mfma_f32_16x16x32_bf16 v[8:11], v[172:175], v[238:241], v[8:11]
	v_mfma_f32_16x16x32_bf16 v[4:7], v[180:183], v[238:241], v[4:7]
	s_setprio 0
	s_setprio 1
	v_mfma_f32_16x16x32_bf16 v[96:99], v[184:187], v[200:203], v[96:99]
	v_mfma_f32_16x16x32_bf16 v[92:95], v[192:195], v[200:203], v[92:95]
	v_mfma_f32_16x16x32_bf16 v[88:91], v[184:187], v[208:211], v[88:91]
	v_mfma_f32_16x16x32_bf16 v[84:87], v[192:195], v[208:211], v[84:87]
	v_mfma_f32_16x16x32_bf16 v[80:83], v[184:187], v[216:219], v[80:83]
	v_mfma_f32_16x16x32_bf16 v[76:79], v[192:195], v[216:219], v[76:79]
	v_mfma_f32_16x16x32_bf16 v[16:19], v[184:187], v[224:227], v[16:19]
	v_mfma_f32_16x16x32_bf16 v[12:15], v[192:195], v[224:227], v[12:15]
	v_mfma_f32_16x16x32_bf16 v[96:99], v[188:191], v[204:207], v[96:99]
	v_mfma_f32_16x16x32_bf16 v[92:95], v[196:199], v[204:207], v[92:95]
	v_mfma_f32_16x16x32_bf16 v[88:91], v[188:191], v[212:215], v[88:91]
	v_mfma_f32_16x16x32_bf16 v[84:87], v[196:199], v[212:215], v[84:87]
	v_mfma_f32_16x16x32_bf16 v[80:83], v[188:191], v[220:223], v[80:83]
	v_mfma_f32_16x16x32_bf16 v[76:79], v[196:199], v[220:223], v[76:79]
	v_mfma_f32_16x16x32_bf16 v[16:19], v[188:191], v[238:241], v[16:19]
	v_mfma_f32_16x16x32_bf16 v[12:15], v[196:199], v[238:241], v[12:15]
	s_setprio 0
	s_barrier
	s_add_i32 s55, 0, 0x18000
	v_add_u32_e32 v153, s55, v165
	s_add_i32 s56, 0, 0x1c000
	ds_read_b128 v[166:169], v153
	ds_read_b128 v[172:175], v153 offset:1024
	ds_read_b128 v[176:179], v153 offset:2048
	ds_read_b128 v[180:183], v153 offset:3072
	v_add_u32_e32 v153, s56, v165
	ds_read_b128 v[184:187], v153
	ds_read_b128 v[188:191], v153 offset:1024
	ds_read_b128 v[192:195], v153 offset:2048
	ds_read_b128 v[196:199], v153 offset:3072
	s_add_u32 s36, s36, 0x40000
	s_addc_u32 s37, s37, 0
	s_mov_b32 m0, s45
	v_lshl_add_u64 v[244:245], s[36:37], 0, v[0:1]
	ds_read_b128 v[200:203], v171 offset:32768
	ds_read_b128 v[204:207], v171 offset:33792
	ds_read_b128 v[208:211], v171 offset:34816
	ds_read_b128 v[212:215], v171 offset:35840
	ds_read_b128 v[216:219], v171 offset:36864
	ds_read_b128 v[220:223], v171 offset:37888
	ds_read_b128 v[224:227], v171 offset:38912
	ds_read_b128 v[238:241], v171 offset:39936
	global_load_lds_dwordx4 v[244:245], off
	v_lshl_add_u64 v[244:245], s[36:37], 0, v[134:135]
	s_mov_b32 m0, s46
	s_nop 0
	global_load_lds_dwordx4 v[244:245], off
	s_waitcnt vmcnt(8)
	s_waitcnt lgkmcnt(0)
	s_barrier
	s_setprio 1
	s_waitcnt lgkmcnt(0)
	v_mfma_f32_16x16x32_bf16 v[72:75], v[166:169], v[200:203], v[72:75]
	v_mfma_f32_16x16x32_bf16 v[68:71], v[176:179], v[200:203], v[68:71]
	v_mfma_f32_16x16x32_bf16 v[64:67], v[166:169], v[208:211], v[64:67]
	v_mfma_f32_16x16x32_bf16 v[60:63], v[176:179], v[208:211], v[60:63]
	v_mfma_f32_16x16x32_bf16 v[56:59], v[166:169], v[216:219], v[56:59]
	v_mfma_f32_16x16x32_bf16 v[52:55], v[176:179], v[216:219], v[52:55]
	v_mfma_f32_16x16x32_bf16 v[48:51], v[166:169], v[224:227], v[48:51]
	v_mfma_f32_16x16x32_bf16 v[44:47], v[176:179], v[224:227], v[44:47]
	v_mfma_f32_16x16x32_bf16 v[72:75], v[172:175], v[204:207], v[72:75]
	v_mfma_f32_16x16x32_bf16 v[68:71], v[180:183], v[204:207], v[68:71]
	v_mfma_f32_16x16x32_bf16 v[64:67], v[172:175], v[212:215], v[64:67]
	v_mfma_f32_16x16x32_bf16 v[60:63], v[180:183], v[212:215], v[60:63]
	v_mfma_f32_16x16x32_bf16 v[56:59], v[172:175], v[220:223], v[56:59]
	v_mfma_f32_16x16x32_bf16 v[52:55], v[180:183], v[220:223], v[52:55]
	v_mfma_f32_16x16x32_bf16 v[48:51], v[172:175], v[238:241], v[48:51]
	v_mfma_f32_16x16x32_bf16 v[44:47], v[180:183], v[238:241], v[44:47]
	s_setprio 0
	s_setprio 1
	v_mfma_f32_16x16x32_bf16 v[128:131], v[184:187], v[200:203], v[128:131]
	v_mfma_f32_16x16x32_bf16 v[124:127], v[192:195], v[200:203], v[124:127]
	v_mfma_f32_16x16x32_bf16 v[120:123], v[184:187], v[208:211], v[120:123]
	v_mfma_f32_16x16x32_bf16 v[116:119], v[192:195], v[208:211], v[116:119]
	v_mfma_f32_16x16x32_bf16 v[112:115], v[184:187], v[216:219], v[112:115]
	v_mfma_f32_16x16x32_bf16 v[108:111], v[192:195], v[216:219], v[108:111]
	v_mfma_f32_16x16x32_bf16 v[104:107], v[184:187], v[224:227], v[104:107]
	v_mfma_f32_16x16x32_bf16 v[100:103], v[192:195], v[224:227], v[100:103]
	v_mfma_f32_16x16x32_bf16 v[128:131], v[188:191], v[204:207], v[128:131]
	v_mfma_f32_16x16x32_bf16 v[124:127], v[196:199], v[204:207], v[124:127]
	v_mfma_f32_16x16x32_bf16 v[120:123], v[188:191], v[212:215], v[120:123]
	v_mfma_f32_16x16x32_bf16 v[116:119], v[196:199], v[212:215], v[116:119]
	v_mfma_f32_16x16x32_bf16 v[112:115], v[188:191], v[220:223], v[112:115]
	v_mfma_f32_16x16x32_bf16 v[108:111], v[196:199], v[220:223], v[108:111]
	v_mfma_f32_16x16x32_bf16 v[104:107], v[188:191], v[238:241], v[104:107]
	v_mfma_f32_16x16x32_bf16 v[100:103], v[196:199], v[238:241], v[100:103]
	s_setprio 0
	s_barrier
; #define PG8_STAGE(bufoff, gbase, voff) do { _Pragma("unroll") for (int _i = 0; _i < 2; ++_i) \
;         __builtin_amdgcn_global_load_lds((const unsigned*)((const char*)(gbase) + (voff)[_i]), (PG8_LAS unsigned*)(lds + (bufoff) + ldsw + _i * 8192), 16, 0, 0); } while (0)
; #define PG8_LDA(dst, b, h) do { _Pragma("unroll") for (int m = 0; m < 4; ++m) _Pragma("unroll") for (int k = 0; k < 2; ++k) dst[m][k] = *(const PG8_LAS bf16x8*)(lds + PG8_SA(b, h) + aoff + m * 2048 + k * 1024); } while (0)
; #define PG8_MMA(ai, bj, At, Bt) do { __builtin_amdgcn_s_setprio(1); _Pragma("unroll") for (int m = 0; m < 4; ++m) _Pragma("unroll") for (int n = 0; n < 2; ++n) _Pragma("unroll") for (int k = 0; k < 2; ++k) \
;         acc[ai][bj][m][n] = __builtin_amdgcn_mfma_f32_16x16x32_bf16(Bt[n][k], At[m][k], acc[ai][bj][m][n], 0, 0, 0); __builtin_amdgcn_s_setprio(0); } while (0)
; #define PG8_WAIT_V(n) asm volatile("s_waitcnt vmcnt(" #n ")" ::: "memory")
; #define PG8_WAIT_L(n) asm volatile("s_waitcnt lgkmcnt(" #n ")" ::: "memory")
; #define PG8_BAR __builtin_amdgcn_s_barrier()
; #define PG8_SCHED __builtin_amdgcn_sched_barrier(0)
; template <class Epi, class Sched, bool ALIGN_EPI = false, bool SP2 = false>
; __device__ __forceinline__ void gemm_phase(PG8_LAS unsigned char* lds, const Gemm g, const Sched& S, const Epi& E, const int tid) {
;     ...
;         for (int t = 0; t < nt; t += 2) {
;     ...
;             PG8_WAIT_V(8); PG8_WAIT_L(0); PG8_BAR; PG8_MMA(0, 0, At, B0); PG8_MMA(0, 1, At, B1); PG8_BAR; PG8_SCHED;
;             PG8_LDA(At, 1, 1); PG8_STAGE(PG8_SB(1, 0), b3, voffB); PG8_STAGE(PG8_SB(1, 1), b3 + hstep, voffB); PG8_STAGE(PG8_SA(1, 0), a3, voffA);
;             PG8_WAIT_V(8); PG8_WAIT_L(0); PG8_BAR; PG8_MMA(1, 0, At, B0); PG8_MMA(1, 1, At, B1); PG8_BAR; PG8_SCHED;
	s_add_i32 s36, s55, s43
	v_lshl_add_u64 v[146:147], v[146:147], 0, s[0:1]
	s_mov_b32 m0, s36
	ds_read_b128 v[200:203], v171 offset:49152
	ds_read_b128 v[204:207], v171 offset:50176
	ds_read_b128 v[208:211], v171 offset:51200
	ds_read_b128 v[212:215], v171 offset:52224
	ds_read_b128 v[216:219], v171 offset:53248
	ds_read_b128 v[220:223], v171 offset:54272
	ds_read_b128 v[224:227], v171 offset:55296
	ds_read_b128 v[238:241], v171 offset:56320
	global_load_lds_dwordx4 v[146:147], off
	s_add_i32 m0, s36, 0x2000
	s_add_u32 s26, s26, 0x40080
	v_lshl_add_u64 v[146:147], v[148:149], 0, s[0:1]
	s_addc_u32 s27, s27, 0
	s_add_i32 s36, s56, s43
	global_load_lds_dwordx4 v[146:147], off
	v_lshl_add_u64 v[146:147], s[26:27], 0, v[132:133]
	s_mov_b32 m0, s36
	s_nop 0
	global_load_lds_dwordx4 v[146:147], off
	v_lshl_add_u64 v[146:147], s[26:27], 0, v[136:137]
	s_add_i32 m0, s36, 0x2000
	s_nop 0
	global_load_lds_dwordx4 v[146:147], off
	v_lshl_add_u64 v[146:147], v[150:151], 0, s[0:1]
	s_mov_b32 m0, s48
	s_nop 0
	global_load_lds_dwordx4 v[146:147], off
	v_lshl_add_u64 v[146:147], v[242:243], 0, s[0:1]
	s_mov_b32 m0, s49
	s_nop 0
	global_load_lds_dwordx4 v[146:147], off
	s_waitcnt vmcnt(8)
	s_waitcnt lgkmcnt(0)
	s_barrier
	s_setprio 1
	s_waitcnt lgkmcnt(0)
	v_mfma_f32_16x16x32_bf16 v[40:43], v[166:169], v[200:203], v[40:43]
	v_mfma_f32_16x16x32_bf16 v[36:39], v[176:179], v[200:203], v[36:39]
	v_mfma_f32_16x16x32_bf16 v[32:35], v[166:169], v[208:211], v[32:35]
	v_mfma_f32_16x16x32_bf16 v[28:31], v[176:179], v[208:211], v[28:31]
	v_mfma_f32_16x16x32_bf16 v[24:27], v[166:169], v[216:219], v[24:27]
	v_mfma_f32_16x16x32_bf16 v[20:23], v[176:179], v[216:219], v[20:23]
	v_mfma_f32_16x16x32_bf16 v[8:11], v[166:169], v[224:227], v[8:11]
	v_mfma_f32_16x16x32_bf16 v[4:7], v[176:179], v[224:227], v[4:7]
	v_mfma_f32_16x16x32_bf16 v[40:43], v[172:175], v[204:207], v[40:43]
	v_mfma_f32_16x16x32_bf16 v[36:39], v[180:183], v[204:207], v[36:39]
	v_mfma_f32_16x16x32_bf16 v[32:35], v[172:175], v[212:215], v[32:35]
	v_mfma_f32_16x16x32_bf16 v[28:31], v[180:183], v[212:215], v[28:31]
	v_mfma_f32_16x16x32_bf16 v[24:27], v[172:175], v[220:223], v[24:27]
	v_mfma_f32_16x16x32_bf16 v[20:23], v[180:183], v[220:223], v[20:23]
	v_mfma_f32_16x16x32_bf16 v[8:11], v[172:175], v[238:241], v[8:11]
	v_mfma_f32_16x16x32_bf16 v[4:7], v[180:183], v[238:241], v[4:7]
	s_setprio 0
	s_setprio 1
	v_mfma_f32_16x16x32_bf16 v[96:99], v[184:187], v[200:203], v[96:99]
	v_mfma_f32_16x16x32_bf16 v[92:95], v[192:195], v[200:203], v[92:95]
	v_mfma_f32_16x16x32_bf16 v[88:91], v[184:187], v[208:211], v[88:91]
	v_mfma_f32_16x16x32_bf16 v[84:87], v[192:195], v[208:211], v[84:87]
	v_mfma_f32_16x16x32_bf16 v[80:83], v[184:187], v[216:219], v[80:83]
	v_mfma_f32_16x16x32_bf16 v[76:79], v[192:195], v[216:219], v[76:79]
	v_mfma_f32_16x16x32_bf16 v[16:19], v[184:187], v[224:227], v[16:19]
	v_mfma_f32_16x16x32_bf16 v[12:15], v[192:195], v[224:227], v[12:15]
	v_mfma_f32_16x16x32_bf16 v[96:99], v[188:191], v[204:207], v[96:99]
	v_mfma_f32_16x16x32_bf16 v[92:95], v[196:199], v[204:207], v[92:95]
	v_mfma_f32_16x16x32_bf16 v[88:91], v[188:191], v[212:215], v[88:91]
	v_mfma_f32_16x16x32_bf16 v[84:87], v[196:199], v[212:215], v[84:87]
	v_mfma_f32_16x16x32_bf16 v[80:83], v[188:191], v[220:223], v[80:83]
	v_mfma_f32_16x16x32_bf16 v[76:79], v[196:199], v[220:223], v[76:79]
	v_mfma_f32_16x16x32_bf16 v[16:19], v[188:191], v[238:241], v[16:19]
	v_mfma_f32_16x16x32_bf16 v[12:15], v[196:199], v[238:241], v[12:15]
	s_setprio 0
	s_add_i32 s54, s54, 2
	s_add_u32 s2, s2, 0x100
	s_addc_u32 s3, s3, 0
	s_add_u32 s52, s52, 0x100
	s_addc_u32 s53, s53, 0
	s_cmp_gt_u32 s54, 13
	s_barrier
	s_cbranch_scc0 .LBB0_293
	s_and_b64 vcc, exec, s[10:11]
	s_cbranch_vccz .LBB0_296
	s_barrier

; #define PG8_STAGE(bufoff, gbase, voff) do { _Pragma("unroll") for (int _i = 0; _i < 2; ++_i) \
;         __builtin_amdgcn_global_load_lds((const unsigned*)((const char*)(gbase) + (voff)[_i]), (PG8_LAS unsigned*)(lds + (bufoff) + ldsw + _i * 8192), 16, 0, 0); } while (0)
; #define PG8_LDA(dst, b, h) do { _Pragma("unroll") for (int m = 0; m < 4; ++m) _Pragma("unroll") for (int k = 0; k < 2; ++k) dst[m][k] = *(const PG8_LAS bf16x8*)(lds + PG8_SA(b, h) + aoff + m * 2048 + k * 1024); } while (0)
; #define PG8_LDB(dst, b, h) do { _Pragma("unroll") for (int n = 0; n < 2; ++n) _Pragma("unroll") for (int k = 0; k < 2; ++k) dst[n][k] = *(const PG8_LAS bf16x8*)(lds + PG8_SB(b, h) + boff + n * 2048 + k * 1024); } while (0)
; #define PG8_MMA(ai, bj, At, Bt) do { __builtin_amdgcn_s_setprio(1); _Pragma("unroll") for (int m = 0; m < 4; ++m) _Pragma("unroll") for (int n = 0; n < 2; ++n) _Pragma("unroll") for (int k = 0; k < 2; ++k) \
;         acc[ai][bj][m][n] = __builtin_amdgcn_mfma_f32_16x16x32_bf16(Bt[n][k], At[m][k], acc[ai][bj][m][n], 0, 0, 0); __builtin_amdgcn_s_setprio(0); } while (0)
; #define PG8_WAIT_V(n) asm volatile("s_waitcnt vmcnt(" #n ")" ::: "memory")
; #define PG8_BAR __builtin_amdgcn_s_barrier()
; template <class Epi, class Sched, bool ALIGN_EPI = false, bool SP2 = false>
; __device__ __forceinline__ void gemm_phase(PG8_LAS unsigned char* lds, const Gemm g, const Sched& S, const Epi& E, const int tid) {
;     ...
;         for (int t = 0; t < nt; t += 2) {
;             const bool last = (t == nt - 2);
;             const char* a1 = cA + (size_t)(t + 1) * kstep;
;             const char* a2 = last ? nA : cA + (size_t)(t + 2) * kstep; const char* b2 = last ? nB : cB + (size_t)(t + 2) * kstep;
;             const char* a3 = a2 + kstep; const char* b3 = b2 + kstep;
;             if (last && has_next) S.a_ready(nxt);
;             if constexpr (SP2) {
;             PG8_LDB(B0, 0, 0); PG8_LDB(B1, 0, 1); PG8_SCHED; PG8_LDA(At, 0, 0); PG8_STAGE(PG8_SA(1, 1), a1 + hstep, voffA);
;             PG8_WAIT_V(8); PG8_WAIT_L(0); PG8_BAR; PG8_MMA(0, 0, At, B0); PG8_MMA(0, 1, At, B1); PG8_BAR; PG8_SCHED;
;             PG8_LDA(At, 0, 1); PG8_STAGE(PG8_SB(0, 0), b2, voffB); PG8_STAGE(PG8_SB(0, 1), b2 + hstep, voffB); PG8_STAGE(PG8_SA(0, 0), a2, voffA);
;             PG8_WAIT_V(8); PG8_WAIT_L(0); PG8_BAR; PG8_MMA(1, 0, At, B0); PG8_MMA(1, 1, At, B1); PG8_BAR; PG8_SCHED;
.LBB0_476:
	s_add_i32 s87, 0, 0x10000
	v_add_u32_e32 v144, s87, v184
	s_add_i32 s81, 0, 0x14000
	ds_read_b128 v[132:135], v144
	ds_read_b128 v[136:139], v144 offset:1024
	ds_read_b128 v[140:143], v144 offset:2048
	ds_read_b128 v[174:177], v144 offset:3072
	v_add_u32_e32 v144, s81, v184
	ds_read_b128 v[178:181], v144
	ds_read_b128 v[188:191], v144 offset:1024
	ds_read_b128 v[192:195], v144 offset:2048
	ds_read_b128 v[196:199], v144 offset:3072
	s_add_i32 s80, s58, 2
	s_add_u32 s98, s6, 0x80
	s_addc_u32 s59, s7, 0
	s_cmp_eq_u32 s70, s58
	s_cselect_b32 s59, s55, s59
	s_cselect_b32 s58, s54, s98
	s_cselect_b32 s83, s57, s79
	s_cselect_b32 s82, s56, s78
	v_lshl_add_u64 v[144:145], s[6:7], 0, v[170:171]
	s_add_i32 m0, s62, 0xc000
	ds_read_b128 v[200:203], v186
	ds_read_b128 v[204:207], v186 offset:1024
	ds_read_b128 v[208:211], v186 offset:2048
	ds_read_b128 v[212:215], v186 offset:3072
	ds_read_b128 v[216:219], v186 offset:4096
	ds_read_b128 v[220:223], v186 offset:5120
	ds_read_b128 v[224:227], v186 offset:6144
	ds_read_b128 v[238:241], v186 offset:7168
	global_load_lds_dwordx4 v[144:145], off
	v_lshl_add_u64 v[144:145], s[6:7], 0, v[172:173]
	s_add_i32 m0, s62, 0xe000
	s_nop 0
	global_load_lds_dwordx4 v[144:145], off
	s_waitcnt vmcnt(8)
	s_waitcnt lgkmcnt(0)
	s_barrier
	s_setprio 1
	s_waitcnt lgkmcnt(0)
	v_mfma_f32_16x16x32_bf16 v[128:131], v[132:135], v[200:203], v[128:131]
	v_mfma_f32_16x16x32_bf16 v[124:127], v[140:143], v[200:203], v[124:127]
	v_mfma_f32_16x16x32_bf16 v[112:115], v[132:135], v[208:211], v[112:115]
	v_mfma_f32_16x16x32_bf16 v[108:111], v[140:143], v[208:211], v[108:111]
	v_mfma_f32_16x16x32_bf16 v[96:99], v[132:135], v[216:219], v[96:99]
	v_mfma_f32_16x16x32_bf16 v[92:95], v[140:143], v[216:219], v[92:95]
	v_mfma_f32_16x16x32_bf16 v[80:83], v[132:135], v[224:227], v[80:83]
	v_mfma_f32_16x16x32_bf16 v[76:79], v[140:143], v[224:227], v[76:79]
	v_mfma_f32_16x16x32_bf16 v[128:131], v[136:139], v[204:207], v[128:131]
	v_mfma_f32_16x16x32_bf16 v[124:127], v[174:177], v[204:207], v[124:127]
	v_mfma_f32_16x16x32_bf16 v[112:115], v[136:139], v[212:215], v[112:115]
	v_mfma_f32_16x16x32_bf16 v[108:111], v[174:177], v[212:215], v[108:111]
	v_mfma_f32_16x16x32_bf16 v[96:99], v[136:139], v[220:223], v[96:99]
	v_mfma_f32_16x16x32_bf16 v[92:95], v[174:177], v[220:223], v[92:95]
	v_mfma_f32_16x16x32_bf16 v[80:83], v[136:139], v[238:241], v[80:83]
	v_mfma_f32_16x16x32_bf16 v[76:79], v[174:177], v[238:241], v[76:79]
	s_setprio 0
	s_setprio 1
	v_mfma_f32_16x16x32_bf16 v[120:123], v[178:181], v[200:203], v[120:123]
	v_mfma_f32_16x16x32_bf16 v[116:119], v[192:195], v[200:203], v[116:119]
	v_mfma_f32_16x16x32_bf16 v[104:107], v[178:181], v[208:211], v[104:107]
	v_mfma_f32_16x16x32_bf16 v[100:103], v[192:195], v[208:211], v[100:103]
	v_mfma_f32_16x16x32_bf16 v[88:91], v[178:181], v[216:219], v[88:91]
	v_mfma_f32_16x16x32_bf16 v[84:87], v[192:195], v[216:219], v[84:87]
	v_mfma_f32_16x16x32_bf16 v[72:75], v[178:181], v[224:227], v[72:75]
	v_mfma_f32_16x16x32_bf16 v[68:71], v[192:195], v[224:227], v[68:71]
	v_mfma_f32_16x16x32_bf16 v[120:123], v[188:191], v[204:207], v[120:123]
	v_mfma_f32_16x16x32_bf16 v[116:119], v[196:199], v[204:207], v[116:119]
	v_mfma_f32_16x16x32_bf16 v[104:107], v[188:191], v[212:215], v[104:107]
	v_mfma_f32_16x16x32_bf16 v[100:103], v[196:199], v[212:215], v[100:103]
	v_mfma_f32_16x16x32_bf16 v[88:91], v[188:191], v[220:223], v[88:91]
	v_mfma_f32_16x16x32_bf16 v[84:87], v[196:199], v[220:223], v[84:87]
	v_mfma_f32_16x16x32_bf16 v[72:75], v[188:191], v[238:241], v[72:75]
	v_mfma_f32_16x16x32_bf16 v[68:71], v[196:199], v[238:241], v[68:71]
	s_setprio 0
	s_barrier
	s_add_i32 s87, s87, s61
	v_lshl_add_u64 v[144:145], s[82:83], 0, v[146:147]
	s_mov_b32 m0, s87
	ds_read_b128 v[200:203], v186 offset:16384
	ds_read_b128 v[204:207], v186 offset:17408
	ds_read_b128 v[208:211], v186 offset:18432
	ds_read_b128 v[212:215], v186 offset:19456
	ds_read_b128 v[216:219], v186 offset:20480
	ds_read_b128 v[220:223], v186 offset:21504
	ds_read_b128 v[224:227], v186 offset:22528
	ds_read_b128 v[238:241], v186 offset:23552
	global_load_lds_dwordx4 v[144:145], off
	s_add_i32 m0, s87, 0x2000
	v_lshl_add_u64 v[242:243], s[82:83], 0, v[168:169]
	s_add_u32 s82, s82, s14
	s_addc_u32 s83, s83, 0
	s_add_i32 s81, s81, s61
	global_load_lds_dwordx4 v[242:243], off
	v_lshl_add_u64 v[244:245], s[82:83], 0, v[146:147]
	s_mov_b32 m0, s81
	v_lshl_add_u64 v[246:247], s[82:83], 0, v[168:169]
	global_load_lds_dwordx4 v[244:245], off
	s_add_i32 m0, s81, 0x2000
	v_lshl_add_u64 v[248:249], s[58:59], 0, v[0:1]
	global_load_lds_dwordx4 v[246:247], off
	s_mov_b32 m0, s62
	v_lshl_add_u64 v[148:149], s[58:59], 0, v[166:167]
	global_load_lds_dwordx4 v[248:249], off
	s_mov_b32 m0, s63
	s_nop 0
	global_load_lds_dwordx4 v[148:149], off
	s_waitcnt vmcnt(8)
	s_waitcnt lgkmcnt(0)
	s_barrier
; #define PG8_STAGE(bufoff, gbase, voff) do { _Pragma("unroll") for (int _i = 0; _i < 2; ++_i) \
;         __builtin_amdgcn_global_load_lds((const unsigned*)((const char*)(gbase) + (voff)[_i]), (PG8_LAS unsigned*)(lds + (bufoff) + ldsw + _i * 8192), 16, 0, 0); } while (0)
; #define PG8_LDA(dst, b, h) do { _Pragma("unroll") for (int m = 0; m < 4; ++m) _Pragma("unroll") for (int k = 0; k < 2; ++k) dst[m][k] = *(const PG8_LAS bf16x8*)(lds + PG8_SA(b, h) + aoff + m * 2048 + k * 1024); } while (0)
; #define PG8_LDB(dst, b, h) do { _Pragma("unroll") for (int n = 0; n < 2; ++n) _Pragma("unroll") for (int k = 0; k < 2; ++k) dst[n][k] = *(const PG8_LAS bf16x8*)(lds + PG8_SB(b, h) + boff + n * 2048 + k * 1024); } while (0)
; #define PG8_MMA(ai, bj, At, Bt) do { __builtin_amdgcn_s_setprio(1); _Pragma("unroll") for (int m = 0; m < 4; ++m) _Pragma("unroll") for (int n = 0; n < 2; ++n) _Pragma("unroll") for (int k = 0; k < 2; ++k) \
;         acc[ai][bj][m][n] = __builtin_amdgcn_mfma_f32_16x16x32_bf16(Bt[n][k], At[m][k], acc[ai][bj][m][n], 0, 0, 0); __builtin_amdgcn_s_setprio(0); } while (0)
; #define PG8_WAIT_V(n) asm volatile("s_waitcnt vmcnt(" #n ")" ::: "memory")
; #define PG8_WAIT_L(n) asm volatile("s_waitcnt lgkmcnt(" #n ")" ::: "memory")
; #define PG8_BAR __builtin_amdgcn_s_barrier()
; #define PG8_SCHED __builtin_amdgcn_sched_barrier(0)
; template <class Epi, class Sched, bool ALIGN_EPI = false, bool SP2 = false>
; __device__ __forceinline__ void gemm_phase(PG8_LAS unsigned char* lds, const Gemm g, const Sched& S, const Epi& E, const int tid) {
;     ...
;             PG8_WAIT_V(8); PG8_WAIT_L(0); PG8_BAR; PG8_MMA(1, 0, At, B0); PG8_MMA(1, 1, At, B1); PG8_BAR; PG8_SCHED;
;             PG8_LDB(B0, 1, 0); PG8_LDB(B1, 1, 1); PG8_SCHED; PG8_LDA(At, 1, 0); PG8_STAGE(PG8_SA(0, 1), a2 + hstep, voffA);
;             PG8_WAIT_V(8); PG8_WAIT_L(0); PG8_BAR; PG8_MMA(0, 0, At, B0); PG8_MMA(0, 1, At, B1); PG8_BAR; PG8_SCHED;
	s_setprio 1
	s_waitcnt lgkmcnt(0)
	v_mfma_f32_16x16x32_bf16 v[64:67], v[132:135], v[200:203], v[64:67]
	v_mfma_f32_16x16x32_bf16 v[60:63], v[140:143], v[200:203], v[60:63]
	v_mfma_f32_16x16x32_bf16 v[48:51], v[132:135], v[208:211], v[48:51]
	v_mfma_f32_16x16x32_bf16 v[44:47], v[140:143], v[208:211], v[44:47]
	v_mfma_f32_16x16x32_bf16 v[32:35], v[132:135], v[216:219], v[32:35]
	v_mfma_f32_16x16x32_bf16 v[28:31], v[140:143], v[216:219], v[28:31]
	v_mfma_f32_16x16x32_bf16 v[16:19], v[132:135], v[224:227], v[16:19]
	v_mfma_f32_16x16x32_bf16 v[12:15], v[140:143], v[224:227], v[12:15]
	v_mfma_f32_16x16x32_bf16 v[64:67], v[136:139], v[204:207], v[64:67]
	v_mfma_f32_16x16x32_bf16 v[60:63], v[174:177], v[204:207], v[60:63]
	v_mfma_f32_16x16x32_bf16 v[48:51], v[136:139], v[212:215], v[48:51]
	v_mfma_f32_16x16x32_bf16 v[44:47], v[174:177], v[212:215], v[44:47]
	v_mfma_f32_16x16x32_bf16 v[32:35], v[136:139], v[220:223], v[32:35]
	v_mfma_f32_16x16x32_bf16 v[28:31], v[174:177], v[220:223], v[28:31]
	v_mfma_f32_16x16x32_bf16 v[16:19], v[136:139], v[238:241], v[16:19]
	v_mfma_f32_16x16x32_bf16 v[12:15], v[174:177], v[238:241], v[12:15]
	s_setprio 0
	s_setprio 1
	v_mfma_f32_16x16x32_bf16 v[56:59], v[178:181], v[200:203], v[56:59]
	v_mfma_f32_16x16x32_bf16 v[52:55], v[192:195], v[200:203], v[52:55]
	v_mfma_f32_16x16x32_bf16 v[40:43], v[178:181], v[208:211], v[40:43]
	v_mfma_f32_16x16x32_bf16 v[36:39], v[192:195], v[208:211], v[36:39]
	v_mfma_f32_16x16x32_bf16 v[24:27], v[178:181], v[216:219], v[24:27]
	v_mfma_f32_16x16x32_bf16 v[20:23], v[192:195], v[216:219], v[20:23]
	v_mfma_f32_16x16x32_bf16 v[8:11], v[178:181], v[224:227], v[8:11]
	v_mfma_f32_16x16x32_bf16 v[4:7], v[192:195], v[224:227], v[4:7]
	v_mfma_f32_16x16x32_bf16 v[56:59], v[188:191], v[204:207], v[56:59]
	v_mfma_f32_16x16x32_bf16 v[52:55], v[196:199], v[204:207], v[52:55]
	v_mfma_f32_16x16x32_bf16 v[40:43], v[188:191], v[212:215], v[40:43]
	v_mfma_f32_16x16x32_bf16 v[36:39], v[196:199], v[212:215], v[36:39]
	v_mfma_f32_16x16x32_bf16 v[24:27], v[188:191], v[220:223], v[24:27]
	v_mfma_f32_16x16x32_bf16 v[20:23], v[196:199], v[220:223], v[20:23]
	v_mfma_f32_16x16x32_bf16 v[8:11], v[188:191], v[238:241], v[8:11]
	v_mfma_f32_16x16x32_bf16 v[4:7], v[196:199], v[238:241], v[4:7]
	s_setprio 0
	s_barrier
	s_add_i32 s81, 0, 0x18000
	v_add_u32_e32 v150, s81, v184
	s_add_i32 s82, 0, 0x1c000
	ds_read_b128 v[132:135], v150
	ds_read_b128 v[136:139], v150 offset:1024
	ds_read_b128 v[140:143], v150 offset:2048
	ds_read_b128 v[174:177], v150 offset:3072
	v_add_u32_e32 v150, s82, v184
	ds_read_b128 v[178:181], v150
	ds_read_b128 v[188:191], v150 offset:1024
	ds_read_b128 v[192:195], v150 offset:2048
	ds_read_b128 v[196:199], v150 offset:3072
	s_add_u32 s58, s58, s14
	s_addc_u32 s59, s59, 0
	s_mov_b32 m0, s64
	v_lshl_add_u64 v[150:151], s[58:59], 0, v[0:1]
	ds_read_b128 v[200:203], v186 offset:32768
	ds_read_b128 v[204:207], v186 offset:33792
	ds_read_b128 v[208:211], v186 offset:34816
	ds_read_b128 v[212:215], v186 offset:35840
	ds_read_b128 v[216:219], v186 offset:36864
	ds_read_b128 v[220:223], v186 offset:37888
	ds_read_b128 v[224:227], v186 offset:38912
	ds_read_b128 v[238:241], v186 offset:39936
	global_load_lds_dwordx4 v[150:151], off
	v_lshl_add_u64 v[150:151], s[58:59], 0, v[166:167]
	s_mov_b32 m0, s65
	s_nop 0
	global_load_lds_dwordx4 v[150:151], off
	s_waitcnt vmcnt(8)
	s_waitcnt lgkmcnt(0)
	s_barrier
	s_setprio 1
	s_waitcnt lgkmcnt(0)
	v_mfma_f32_16x16x32_bf16 v[128:131], v[132:135], v[200:203], v[128:131]
	v_mfma_f32_16x16x32_bf16 v[124:127], v[140:143], v[200:203], v[124:127]
	v_mfma_f32_16x16x32_bf16 v[112:115], v[132:135], v[208:211], v[112:115]
	v_mfma_f32_16x16x32_bf16 v[108:111], v[140:143], v[208:211], v[108:111]
	v_mfma_f32_16x16x32_bf16 v[96:99], v[132:135], v[216:219], v[96:99]
	v_mfma_f32_16x16x32_bf16 v[92:95], v[140:143], v[216:219], v[92:95]
	v_mfma_f32_16x16x32_bf16 v[80:83], v[132:135], v[224:227], v[80:83]
	v_mfma_f32_16x16x32_bf16 v[76:79], v[140:143], v[224:227], v[76:79]
	v_mfma_f32_16x16x32_bf16 v[128:131], v[136:139], v[204:207], v[128:131]
	v_mfma_f32_16x16x32_bf16 v[124:127], v[174:177], v[204:207], v[124:127]
	v_mfma_f32_16x16x32_bf16 v[112:115], v[136:139], v[212:215], v[112:115]
	v_mfma_f32_16x16x32_bf16 v[108:111], v[174:177], v[212:215], v[108:111]
	v_mfma_f32_16x16x32_bf16 v[96:99], v[136:139], v[220:223], v[96:99]
	v_mfma_f32_16x16x32_bf16 v[92:95], v[174:177], v[220:223], v[92:95]
	v_mfma_f32_16x16x32_bf16 v[80:83], v[136:139], v[238:241], v[80:83]
	v_mfma_f32_16x16x32_bf16 v[76:79], v[174:177], v[238:241], v[76:79]
	s_setprio 0
	s_setprio 1
	v_mfma_f32_16x16x32_bf16 v[120:123], v[178:181], v[200:203], v[120:123]
	v_mfma_f32_16x16x32_bf16 v[116:119], v[192:195], v[200:203], v[116:119]
	v_mfma_f32_16x16x32_bf16 v[104:107], v[178:181], v[208:211], v[104:107]
	v_mfma_f32_16x16x32_bf16 v[100:103], v[192:195], v[208:211], v[100:103]
	v_mfma_f32_16x16x32_bf16 v[88:91], v[178:181], v[216:219], v[88:91]
	v_mfma_f32_16x16x32_bf16 v[84:87], v[192:195], v[216:219], v[84:87]
	v_mfma_f32_16x16x32_bf16 v[72:75], v[178:181], v[224:227], v[72:75]
	v_mfma_f32_16x16x32_bf16 v[68:71], v[192:195], v[224:227], v[68:71]
	v_mfma_f32_16x16x32_bf16 v[120:123], v[188:191], v[204:207], v[120:123]
	v_mfma_f32_16x16x32_bf16 v[116:119], v[196:199], v[204:207], v[116:119]
	v_mfma_f32_16x16x32_bf16 v[104:107], v[188:191], v[212:215], v[104:107]
	v_mfma_f32_16x16x32_bf16 v[100:103], v[196:199], v[212:215], v[100:103]
	v_mfma_f32_16x16x32_bf16 v[88:91], v[188:191], v[220:223], v[88:91]
	v_mfma_f32_16x16x32_bf16 v[84:87], v[196:199], v[220:223], v[84:87]
	v_mfma_f32_16x16x32_bf16 v[72:75], v[188:191], v[238:241], v[72:75]
	v_mfma_f32_16x16x32_bf16 v[68:71], v[196:199], v[238:241], v[68:71]
	s_setprio 0
	s_barrier
; #define PG8_STAGE(bufoff, gbase, voff) do { _Pragma("unroll") for (int _i = 0; _i < 2; ++_i) \
;         __builtin_amdgcn_global_load_lds((const unsigned*)((const char*)(gbase) + (voff)[_i]), (PG8_LAS unsigned*)(lds + (bufoff) + ldsw + _i * 8192), 16, 0, 0); } while (0)
; #define PG8_LDA(dst, b, h) do { _Pragma("unroll") for (int m = 0; m < 4; ++m) _Pragma("unroll") for (int k = 0; k < 2; ++k) dst[m][k] = *(const PG8_LAS bf16x8*)(lds + PG8_SA(b, h) + aoff + m * 2048 + k * 1024); } while (0)
; #define PG8_MMA(ai, bj, At, Bt) do { __builtin_amdgcn_s_setprio(1); _Pragma("unroll") for (int m = 0; m < 4; ++m) _Pragma("unroll") for (int n = 0; n < 2; ++n) _Pragma("unroll") for (int k = 0; k < 2; ++k) \
;         acc[ai][bj][m][n] = __builtin_amdgcn_mfma_f32_16x16x32_bf16(Bt[n][k], At[m][k], acc[ai][bj][m][n], 0, 0, 0); __builtin_amdgcn_s_setprio(0); } while (0)
; #define PG8_WAIT_V(n) asm volatile("s_waitcnt vmcnt(" #n ")" ::: "memory")
; #define PG8_WAIT_L(n) asm volatile("s_waitcnt lgkmcnt(" #n ")" ::: "memory")
; #define PG8_BAR __builtin_amdgcn_s_barrier()
; #define PG8_SCHED __builtin_amdgcn_sched_barrier(0)
; template <class Epi, class Sched, bool ALIGN_EPI = false, bool SP2 = false>
; __device__ __forceinline__ void gemm_phase(PG8_LAS unsigned char* lds, const Gemm g, const Sched& S, const Epi& E, const int tid) {
;     ...
;         for (int t = 0; t < nt; t += 2) {
;     ...
;             PG8_WAIT_V(8); PG8_WAIT_L(0); PG8_BAR; PG8_MMA(0, 0, At, B0); PG8_MMA(0, 1, At, B1); PG8_BAR; PG8_SCHED;
;             PG8_LDA(At, 1, 1); PG8_STAGE(PG8_SB(1, 0), b3, voffB); PG8_STAGE(PG8_SB(1, 1), b3 + hstep, voffB); PG8_STAGE(PG8_SA(1, 0), a3, voffA);
;             PG8_WAIT_V(8); PG8_WAIT_L(0); PG8_BAR; PG8_MMA(1, 0, At, B0); PG8_MMA(1, 1, At, B1); PG8_BAR; PG8_SCHED;
	s_add_i32 s58, s81, s61
	v_lshl_add_u64 v[144:145], v[144:145], 0, s[0:1]
	s_mov_b32 m0, s58
	ds_read_b128 v[200:203], v186 offset:49152
	ds_read_b128 v[204:207], v186 offset:50176
	ds_read_b128 v[208:211], v186 offset:51200
	ds_read_b128 v[212:215], v186 offset:52224
	ds_read_b128 v[216:219], v186 offset:53248
	ds_read_b128 v[220:223], v186 offset:54272
	ds_read_b128 v[224:227], v186 offset:55296
	ds_read_b128 v[238:241], v186 offset:56320
	global_load_lds_dwordx4 v[144:145], off
	v_lshl_add_u64 v[144:145], v[242:243], 0, s[0:1]
	s_add_i32 m0, s58, 0x2000
	s_add_i32 s58, s82, s61
	global_load_lds_dwordx4 v[144:145], off
	v_lshl_add_u64 v[144:145], v[244:245], 0, s[0:1]
	s_mov_b32 m0, s58
	s_nop 0
	global_load_lds_dwordx4 v[144:145], off
	v_lshl_add_u64 v[144:145], v[246:247], 0, s[0:1]
	s_add_i32 m0, s58, 0x2000
	s_nop 0
	global_load_lds_dwordx4 v[144:145], off
	v_lshl_add_u64 v[144:145], v[248:249], 0, s[0:1]
	s_mov_b32 m0, s66
	s_nop 0
	global_load_lds_dwordx4 v[144:145], off
	v_lshl_add_u64 v[144:145], v[148:149], 0, s[0:1]
	s_mov_b32 m0, s67
	s_nop 0
	global_load_lds_dwordx4 v[144:145], off
	s_waitcnt vmcnt(8)
	s_waitcnt lgkmcnt(0)
	s_barrier
	s_setprio 1
	s_waitcnt lgkmcnt(0)
	v_mfma_f32_16x16x32_bf16 v[64:67], v[132:135], v[200:203], v[64:67]
	v_mfma_f32_16x16x32_bf16 v[60:63], v[140:143], v[200:203], v[60:63]
	v_mfma_f32_16x16x32_bf16 v[48:51], v[132:135], v[208:211], v[48:51]
	v_mfma_f32_16x16x32_bf16 v[44:47], v[140:143], v[208:211], v[44:47]
	v_mfma_f32_16x16x32_bf16 v[32:35], v[132:135], v[216:219], v[32:35]
	v_mfma_f32_16x16x32_bf16 v[28:31], v[140:143], v[216:219], v[28:31]
	v_mfma_f32_16x16x32_bf16 v[16:19], v[132:135], v[224:227], v[16:19]
	v_mfma_f32_16x16x32_bf16 v[12:15], v[140:143], v[224:227], v[12:15]
	v_mfma_f32_16x16x32_bf16 v[64:67], v[136:139], v[204:207], v[64:67]
	v_mfma_f32_16x16x32_bf16 v[60:63], v[174:177], v[204:207], v[60:63]
	v_mfma_f32_16x16x32_bf16 v[48:51], v[136:139], v[212:215], v[48:51]
	v_mfma_f32_16x16x32_bf16 v[44:47], v[174:177], v[212:215], v[44:47]
	v_mfma_f32_16x16x32_bf16 v[32:35], v[136:139], v[220:223], v[32:35]
	v_mfma_f32_16x16x32_bf16 v[28:31], v[174:177], v[220:223], v[28:31]
	v_mfma_f32_16x16x32_bf16 v[16:19], v[136:139], v[238:241], v[16:19]
	v_mfma_f32_16x16x32_bf16 v[12:15], v[174:177], v[238:241], v[12:15]
	s_setprio 0
	s_setprio 1
	v_mfma_f32_16x16x32_bf16 v[56:59], v[178:181], v[200:203], v[56:59]
	v_mfma_f32_16x16x32_bf16 v[52:55], v[192:195], v[200:203], v[52:55]
	v_mfma_f32_16x16x32_bf16 v[40:43], v[178:181], v[208:211], v[40:43]
	v_mfma_f32_16x16x32_bf16 v[36:39], v[192:195], v[208:211], v[36:39]
	v_mfma_f32_16x16x32_bf16 v[24:27], v[178:181], v[216:219], v[24:27]
	v_mfma_f32_16x16x32_bf16 v[20:23], v[192:195], v[216:219], v[20:23]
	v_mfma_f32_16x16x32_bf16 v[8:11], v[178:181], v[224:227], v[8:11]
	v_mfma_f32_16x16x32_bf16 v[4:7], v[192:195], v[224:227], v[4:7]
	v_mfma_f32_16x16x32_bf16 v[56:59], v[188:191], v[204:207], v[56:59]
	v_mfma_f32_16x16x32_bf16 v[52:55], v[196:199], v[204:207], v[52:55]
	v_mfma_f32_16x16x32_bf16 v[40:43], v[188:191], v[212:215], v[40:43]
	v_mfma_f32_16x16x32_bf16 v[36:39], v[196:199], v[212:215], v[36:39]
	v_mfma_f32_16x16x32_bf16 v[24:27], v[188:191], v[220:223], v[24:27]
	v_mfma_f32_16x16x32_bf16 v[20:23], v[196:199], v[220:223], v[20:23]
	v_mfma_f32_16x16x32_bf16 v[8:11], v[188:191], v[238:241], v[8:11]
	v_mfma_f32_16x16x32_bf16 v[4:7], v[196:199], v[238:241], v[4:7]
	s_setprio 0
	s_add_u32 s6, s6, 0x100
	s_addc_u32 s7, s7, 0
	s_add_u32 s78, s78, 0x100
	s_addc_u32 s79, s79, 0
	s_cmp_ge_u32 s80, s69
	s_mov_b32 s58, s80
	s_barrier
	s_cbranch_scc0 .LBB0_476
	s_and_b64 vcc, exec, s[50:51]
	s_cbranch_vccz .LBB0_479
	s_barrier

; #define PG8_STAGE(bufoff, gbase, voff) do { _Pragma("unroll") for (int _i = 0; _i < 2; ++_i) \
;         __builtin_amdgcn_global_load_lds((const unsigned*)((const char*)(gbase) + (voff)[_i]), (PG8_LAS unsigned*)(lds + (bufoff) + ldsw + _i * 8192), 16, 0, 0); } while (0)
; #define PG8_LDA(dst, b, h) do { _Pragma("unroll") for (int m = 0; m < 4; ++m) _Pragma("unroll") for (int k = 0; k < 2; ++k) dst[m][k] = *(const PG8_LAS bf16x8*)(lds + PG8_SA(b, h) + aoff + m * 2048 + k * 1024); } while (0)
; #define PG8_LDB(dst, b, h) do { _Pragma("unroll") for (int n = 0; n < 2; ++n) _Pragma("unroll") for (int k = 0; k < 2; ++k) dst[n][k] = *(const PG8_LAS bf16x8*)(lds + PG8_SB(b, h) + boff + n * 2048 + k * 1024); } while (0)
; #define PG8_MMA(ai, bj, At, Bt) do { __builtin_amdgcn_s_setprio(1); _Pragma("unroll") for (int m = 0; m < 4; ++m) _Pragma("unroll") for (int n = 0; n < 2; ++n) _Pragma("unroll") for (int k = 0; k < 2; ++k) \
;         acc[ai][bj][m][n] = __builtin_amdgcn_mfma_f32_16x16x32_bf16(Bt[n][k], At[m][k], acc[ai][bj][m][n], 0, 0, 0); __builtin_amdgcn_s_setprio(0); } while (0)
; #define PG8_WAIT_V(n) asm volatile("s_waitcnt vmcnt(" #n ")" ::: "memory")
; #define PG8_BAR __builtin_amdgcn_s_barrier()
; template <class Epi, class Sched, bool ALIGN_EPI = false, bool SP2 = false>
; __device__ __forceinline__ void gemm_phase(PG8_LAS unsigned char* lds, const Gemm g, const Sched& S, const Epi& E, const int tid) {
;     ...
;         for (int t = 0; t < nt; t += 2) {
;             const bool last = (t == nt - 2);
;             const char* a1 = cA + (size_t)(t + 1) * kstep;
;             const char* a2 = last ? nA : cA + (size_t)(t + 2) * kstep; const char* b2 = last ? nB : cB + (size_t)(t + 2) * kstep;
;             const char* a3 = a2 + kstep; const char* b3 = b2 + kstep;
;             if (last && has_next) S.a_ready(nxt);
;             if constexpr (SP2) {
;             PG8_LDB(B0, 0, 0); PG8_LDB(B1, 0, 1); PG8_SCHED; PG8_LDA(At, 0, 0); PG8_STAGE(PG8_SA(1, 1), a1 + hstep, voffA);
;             PG8_WAIT_V(8); PG8_WAIT_L(0); PG8_BAR; PG8_MMA(0, 0, At, B0); PG8_MMA(0, 1, At, B1); PG8_BAR; PG8_SCHED;
;             PG8_LDA(At, 0, 1); PG8_STAGE(PG8_SB(0, 0), b2, voffB); PG8_STAGE(PG8_SB(0, 1), b2 + hstep, voffB); PG8_STAGE(PG8_SA(0, 0), a2, voffA);
;             PG8_WAIT_V(8); PG8_WAIT_L(0); PG8_BAR; PG8_MMA(1, 0, At, B0); PG8_MMA(1, 1, At, B1); PG8_BAR; PG8_SCHED;
.LBB0_522:
	s_add_i32 s52, 0, 0x10000
	v_add_u32_e32 v148, s52, v146
	s_add_i32 s54, 0, 0x14000
	ds_read_b128 v[142:145], v148
	ds_read_b128 v[166:169], v148 offset:1024
	ds_read_b128 v[170:173], v148 offset:2048
	ds_read_b128 v[174:177], v148 offset:3072
	v_add_u32_e32 v148, s54, v146
	ds_read_b128 v[178:181], v148
	ds_read_b128 v[182:185], v148 offset:1024
	ds_read_b128 v[186:189], v148 offset:2048
	ds_read_b128 v[190:193], v148 offset:3072
	s_add_u32 s20, s18, 0xfffc0080
	s_addc_u32 s21, s19, -1
	s_cmp_eq_u32 s51, 12
	s_cselect_b32 s23, s13, s21
	s_cselect_b32 s22, s47, s20
	s_cselect_b32 s21, s11, s50
	s_cselect_b32 s20, s48, s49
	v_lshl_add_u64 v[226:227], s[18:19], 0, v[138:139]
	s_add_i32 m0, s38, 0xc000
	ds_read_b128 v[194:197], v153
	ds_read_b128 v[198:201], v153 offset:1024
	ds_read_b128 v[202:205], v153 offset:2048
	ds_read_b128 v[206:209], v153 offset:3072
	ds_read_b128 v[210:213], v153 offset:4096
	ds_read_b128 v[214:217], v153 offset:5120
	ds_read_b128 v[218:221], v153 offset:6144
	ds_read_b128 v[222:225], v153 offset:7168
	global_load_lds_dwordx4 v[226:227], off
	v_lshl_add_u64 v[226:227], s[18:19], 0, v[140:141]
	s_add_i32 m0, s38, 0xe000
	s_nop 0
	global_load_lds_dwordx4 v[226:227], off
	s_waitcnt vmcnt(8)
	s_waitcnt lgkmcnt(0)
	s_barrier
	s_setprio 1
	s_waitcnt lgkmcnt(0)
	v_mfma_f32_16x16x32_bf16 v[128:131], v[142:145], v[194:197], v[128:131]
	v_mfma_f32_16x16x32_bf16 v[120:123], v[170:173], v[194:197], v[120:123]
	v_mfma_f32_16x16x32_bf16 v[112:115], v[142:145], v[202:205], v[112:115]
	v_mfma_f32_16x16x32_bf16 v[104:107], v[170:173], v[202:205], v[104:107]
	v_mfma_f32_16x16x32_bf16 v[96:99], v[142:145], v[210:213], v[96:99]
	v_mfma_f32_16x16x32_bf16 v[88:91], v[170:173], v[210:213], v[88:91]
	v_mfma_f32_16x16x32_bf16 v[80:83], v[142:145], v[218:221], v[80:83]
	v_mfma_f32_16x16x32_bf16 v[72:75], v[170:173], v[218:221], v[72:75]
	v_mfma_f32_16x16x32_bf16 v[128:131], v[166:169], v[198:201], v[128:131]
	v_mfma_f32_16x16x32_bf16 v[120:123], v[174:177], v[198:201], v[120:123]
	v_mfma_f32_16x16x32_bf16 v[112:115], v[166:169], v[206:209], v[112:115]
	v_mfma_f32_16x16x32_bf16 v[104:107], v[174:177], v[206:209], v[104:107]
	v_mfma_f32_16x16x32_bf16 v[96:99], v[166:169], v[214:217], v[96:99]
	v_mfma_f32_16x16x32_bf16 v[88:91], v[174:177], v[214:217], v[88:91]
	v_mfma_f32_16x16x32_bf16 v[80:83], v[166:169], v[222:225], v[80:83]
	v_mfma_f32_16x16x32_bf16 v[72:75], v[174:177], v[222:225], v[72:75]
	s_setprio 0
	s_setprio 1
	v_mfma_f32_16x16x32_bf16 v[124:127], v[178:181], v[194:197], v[124:127]
	v_mfma_f32_16x16x32_bf16 v[116:119], v[186:189], v[194:197], v[116:119]
	v_mfma_f32_16x16x32_bf16 v[108:111], v[178:181], v[202:205], v[108:111]
	v_mfma_f32_16x16x32_bf16 v[100:103], v[186:189], v[202:205], v[100:103]
	v_mfma_f32_16x16x32_bf16 v[92:95], v[178:181], v[210:213], v[92:95]
	v_mfma_f32_16x16x32_bf16 v[84:87], v[186:189], v[210:213], v[84:87]
	v_mfma_f32_16x16x32_bf16 v[76:79], v[178:181], v[218:221], v[76:79]
	v_mfma_f32_16x16x32_bf16 v[68:71], v[186:189], v[218:221], v[68:71]
	v_mfma_f32_16x16x32_bf16 v[124:127], v[182:185], v[198:201], v[124:127]
	v_mfma_f32_16x16x32_bf16 v[116:119], v[190:193], v[198:201], v[116:119]
	v_mfma_f32_16x16x32_bf16 v[108:111], v[182:185], v[206:209], v[108:111]
	v_mfma_f32_16x16x32_bf16 v[100:103], v[190:193], v[206:209], v[100:103]
	v_mfma_f32_16x16x32_bf16 v[92:95], v[182:185], v[214:217], v[92:95]
	v_mfma_f32_16x16x32_bf16 v[84:87], v[190:193], v[214:217], v[84:87]
	v_mfma_f32_16x16x32_bf16 v[76:79], v[182:185], v[222:225], v[76:79]
	v_mfma_f32_16x16x32_bf16 v[68:71], v[190:193], v[222:225], v[68:71]
	s_setprio 0
	s_barrier
	s_add_i32 s52, s52, s37
	v_lshl_add_u64 v[226:227], s[20:21], 0, v[134:135]
	s_mov_b32 m0, s52
	ds_read_b128 v[194:197], v153 offset:16384
	ds_read_b128 v[198:201], v153 offset:17408
	ds_read_b128 v[202:205], v153 offset:18432
	ds_read_b128 v[206:209], v153 offset:19456
	ds_read_b128 v[210:213], v153 offset:20480
	ds_read_b128 v[214:217], v153 offset:21504
	ds_read_b128 v[218:221], v153 offset:22528
	ds_read_b128 v[222:225], v153 offset:23552
	global_load_lds_dwordx4 v[226:227], off
	s_add_i32 m0, s52, 0x2000
	s_add_u32 s52, s20, 0x40000
	v_lshl_add_u64 v[238:239], s[20:21], 0, v[0:1]
	s_addc_u32 s53, s21, 0
	s_add_i32 s54, s54, s37
	global_load_lds_dwordx4 v[238:239], off
	v_lshl_add_u64 v[240:241], s[52:53], 0, v[134:135]
	s_mov_b32 m0, s54
	v_lshl_add_u64 v[242:243], s[22:23], 0, v[132:133]
	global_load_lds_dwordx4 v[240:241], off
	v_lshl_add_u64 v[240:241], s[52:53], 0, v[0:1]
	s_add_i32 m0, s54, 0x2000
	s_nop 0
	global_load_lds_dwordx4 v[240:241], off
	v_lshl_add_u64 v[240:241], s[22:23], 0, v[136:137]
	s_mov_b32 m0, s38
	s_nop 0
	global_load_lds_dwordx4 v[240:241], off
	s_mov_b32 m0, s39
	s_nop 0
	global_load_lds_dwordx4 v[242:243], off
	s_waitcnt vmcnt(8)
	s_waitcnt lgkmcnt(0)
	s_barrier
; #define PG8_STAGE(bufoff, gbase, voff) do { _Pragma("unroll") for (int _i = 0; _i < 2; ++_i) \
;         __builtin_amdgcn_global_load_lds((const unsigned*)((const char*)(gbase) + (voff)[_i]), (PG8_LAS unsigned*)(lds + (bufoff) + ldsw + _i * 8192), 16, 0, 0); } while (0)
; #define PG8_LDA(dst, b, h) do { _Pragma("unroll") for (int m = 0; m < 4; ++m) _Pragma("unroll") for (int k = 0; k < 2; ++k) dst[m][k] = *(const PG8_LAS bf16x8*)(lds + PG8_SA(b, h) + aoff + m * 2048 + k * 1024); } while (0)
; #define PG8_LDB(dst, b, h) do { _Pragma("unroll") for (int n = 0; n < 2; ++n) _Pragma("unroll") for (int k = 0; k < 2; ++k) dst[n][k] = *(const PG8_LAS bf16x8*)(lds + PG8_SB(b, h) + boff + n * 2048 + k * 1024); } while (0)
; #define PG8_MMA(ai, bj, At, Bt) do { __builtin_amdgcn_s_setprio(1); _Pragma("unroll") for (int m = 0; m < 4; ++m) _Pragma("unroll") for (int n = 0; n < 2; ++n) _Pragma("unroll") for (int k = 0; k < 2; ++k) \
;         acc[ai][bj][m][n] = __builtin_amdgcn_mfma_f32_16x16x32_bf16(Bt[n][k], At[m][k], acc[ai][bj][m][n], 0, 0, 0); __builtin_amdgcn_s_setprio(0); } while (0)
; #define PG8_WAIT_V(n) asm volatile("s_waitcnt vmcnt(" #n ")" ::: "memory")
; #define PG8_WAIT_L(n) asm volatile("s_waitcnt lgkmcnt(" #n ")" ::: "memory")
; #define PG8_BAR __builtin_amdgcn_s_barrier()
; #define PG8_SCHED __builtin_amdgcn_sched_barrier(0)
; template <class Epi, class Sched, bool ALIGN_EPI = false, bool SP2 = false>
; __device__ __forceinline__ void gemm_phase(PG8_LAS unsigned char* lds, const Gemm g, const Sched& S, const Epi& E, const int tid) {
;     ...
;             PG8_WAIT_V(8); PG8_WAIT_L(0); PG8_BAR; PG8_MMA(1, 0, At, B0); PG8_MMA(1, 1, At, B1); PG8_BAR; PG8_SCHED;
;             PG8_LDB(B0, 1, 0); PG8_LDB(B1, 1, 1); PG8_SCHED; PG8_LDA(At, 1, 0); PG8_STAGE(PG8_SA(0, 1), a2 + hstep, voffA);
;             PG8_WAIT_V(8); PG8_WAIT_L(0); PG8_BAR; PG8_MMA(0, 0, At, B0); PG8_MMA(0, 1, At, B1); PG8_BAR; PG8_SCHED;
	s_setprio 1
	s_waitcnt lgkmcnt(0)
	v_mfma_f32_16x16x32_bf16 v[64:67], v[142:145], v[194:197], v[64:67]
	v_mfma_f32_16x16x32_bf16 v[56:59], v[170:173], v[194:197], v[56:59]
	v_mfma_f32_16x16x32_bf16 v[48:51], v[142:145], v[202:205], v[48:51]
	v_mfma_f32_16x16x32_bf16 v[40:43], v[170:173], v[202:205], v[40:43]
	v_mfma_f32_16x16x32_bf16 v[32:35], v[142:145], v[210:213], v[32:35]
	v_mfma_f32_16x16x32_bf16 v[24:27], v[170:173], v[210:213], v[24:27]
	v_mfma_f32_16x16x32_bf16 v[16:19], v[142:145], v[218:221], v[16:19]
	v_mfma_f32_16x16x32_bf16 v[8:11], v[170:173], v[218:221], v[8:11]
	v_mfma_f32_16x16x32_bf16 v[64:67], v[166:169], v[198:201], v[64:67]
	v_mfma_f32_16x16x32_bf16 v[56:59], v[174:177], v[198:201], v[56:59]
	v_mfma_f32_16x16x32_bf16 v[48:51], v[166:169], v[206:209], v[48:51]
	v_mfma_f32_16x16x32_bf16 v[40:43], v[174:177], v[206:209], v[40:43]
	v_mfma_f32_16x16x32_bf16 v[32:35], v[166:169], v[214:217], v[32:35]
	v_mfma_f32_16x16x32_bf16 v[24:27], v[174:177], v[214:217], v[24:27]
	v_mfma_f32_16x16x32_bf16 v[16:19], v[166:169], v[222:225], v[16:19]
	v_mfma_f32_16x16x32_bf16 v[8:11], v[174:177], v[222:225], v[8:11]
	s_setprio 0
	s_setprio 1
	v_mfma_f32_16x16x32_bf16 v[60:63], v[178:181], v[194:197], v[60:63]
	v_mfma_f32_16x16x32_bf16 v[52:55], v[186:189], v[194:197], v[52:55]
	v_mfma_f32_16x16x32_bf16 v[44:47], v[178:181], v[202:205], v[44:47]
	v_mfma_f32_16x16x32_bf16 v[36:39], v[186:189], v[202:205], v[36:39]
	v_mfma_f32_16x16x32_bf16 v[28:31], v[178:181], v[210:213], v[28:31]
	v_mfma_f32_16x16x32_bf16 v[20:23], v[186:189], v[210:213], v[20:23]
	v_mfma_f32_16x16x32_bf16 v[12:15], v[178:181], v[218:221], v[12:15]
	v_mfma_f32_16x16x32_bf16 v[4:7], v[186:189], v[218:221], v[4:7]
	v_mfma_f32_16x16x32_bf16 v[60:63], v[182:185], v[198:201], v[60:63]
	v_mfma_f32_16x16x32_bf16 v[52:55], v[190:193], v[198:201], v[52:55]
	v_mfma_f32_16x16x32_bf16 v[44:47], v[182:185], v[206:209], v[44:47]
	v_mfma_f32_16x16x32_bf16 v[36:39], v[190:193], v[206:209], v[36:39]
	v_mfma_f32_16x16x32_bf16 v[28:31], v[182:185], v[214:217], v[28:31]
	v_mfma_f32_16x16x32_bf16 v[20:23], v[190:193], v[214:217], v[20:23]
	v_mfma_f32_16x16x32_bf16 v[12:15], v[182:185], v[222:225], v[12:15]
	v_mfma_f32_16x16x32_bf16 v[4:7], v[190:193], v[222:225], v[4:7]
	s_setprio 0
	s_barrier
	s_add_i32 s52, 0, 0x18000
	v_add_u32_e32 v148, s52, v146
	s_add_i32 s53, 0, 0x1c000
	ds_read_b128 v[142:145], v148
	ds_read_b128 v[166:169], v148 offset:1024
	ds_read_b128 v[170:173], v148 offset:2048
	ds_read_b128 v[174:177], v148 offset:3072
	v_add_u32_e32 v148, s53, v146
	ds_read_b128 v[178:181], v148
	ds_read_b128 v[182:185], v148 offset:1024
	ds_read_b128 v[186:189], v148 offset:2048
	ds_read_b128 v[190:193], v148 offset:3072
	s_add_u32 s22, s22, 0x40000
	s_addc_u32 s23, s23, 0
	s_mov_b32 m0, s40
	v_lshl_add_u64 v[244:245], s[22:23], 0, v[136:137]
	ds_read_b128 v[194:197], v153 offset:32768
	ds_read_b128 v[198:201], v153 offset:33792
	ds_read_b128 v[202:205], v153 offset:34816
	ds_read_b128 v[206:209], v153 offset:35840
	ds_read_b128 v[210:213], v153 offset:36864
	ds_read_b128 v[214:217], v153 offset:37888
	ds_read_b128 v[218:221], v153 offset:38912
	ds_read_b128 v[222:225], v153 offset:39936
	global_load_lds_dwordx4 v[244:245], off
	v_lshl_add_u64 v[244:245], s[22:23], 0, v[132:133]
	s_mov_b32 m0, s41
	s_nop 0
	global_load_lds_dwordx4 v[244:245], off
	s_waitcnt vmcnt(8)
	s_waitcnt lgkmcnt(0)
	s_barrier
	s_setprio 1
	s_waitcnt lgkmcnt(0)
	v_mfma_f32_16x16x32_bf16 v[128:131], v[142:145], v[194:197], v[128:131]
	v_mfma_f32_16x16x32_bf16 v[120:123], v[170:173], v[194:197], v[120:123]
	v_mfma_f32_16x16x32_bf16 v[112:115], v[142:145], v[202:205], v[112:115]
	v_mfma_f32_16x16x32_bf16 v[104:107], v[170:173], v[202:205], v[104:107]
	v_mfma_f32_16x16x32_bf16 v[96:99], v[142:145], v[210:213], v[96:99]
	v_mfma_f32_16x16x32_bf16 v[88:91], v[170:173], v[210:213], v[88:91]
	v_mfma_f32_16x16x32_bf16 v[80:83], v[142:145], v[218:221], v[80:83]
	v_mfma_f32_16x16x32_bf16 v[72:75], v[170:173], v[218:221], v[72:75]
	v_mfma_f32_16x16x32_bf16 v[128:131], v[166:169], v[198:201], v[128:131]
	v_mfma_f32_16x16x32_bf16 v[120:123], v[174:177], v[198:201], v[120:123]
	v_mfma_f32_16x16x32_bf16 v[112:115], v[166:169], v[206:209], v[112:115]
	v_mfma_f32_16x16x32_bf16 v[104:107], v[174:177], v[206:209], v[104:107]
	v_mfma_f32_16x16x32_bf16 v[96:99], v[166:169], v[214:217], v[96:99]
	v_mfma_f32_16x16x32_bf16 v[88:91], v[174:177], v[214:217], v[88:91]
	v_mfma_f32_16x16x32_bf16 v[80:83], v[166:169], v[222:225], v[80:83]
	v_mfma_f32_16x16x32_bf16 v[72:75], v[174:177], v[222:225], v[72:75]
	s_setprio 0
	s_setprio 1
	v_mfma_f32_16x16x32_bf16 v[124:127], v[178:181], v[194:197], v[124:127]
	v_mfma_f32_16x16x32_bf16 v[116:119], v[186:189], v[194:197], v[116:119]
	v_mfma_f32_16x16x32_bf16 v[108:111], v[178:181], v[202:205], v[108:111]
	v_mfma_f32_16x16x32_bf16 v[100:103], v[186:189], v[202:205], v[100:103]
	v_mfma_f32_16x16x32_bf16 v[92:95], v[178:181], v[210:213], v[92:95]
	v_mfma_f32_16x16x32_bf16 v[84:87], v[186:189], v[210:213], v[84:87]
	v_mfma_f32_16x16x32_bf16 v[76:79], v[178:181], v[218:221], v[76:79]
	v_mfma_f32_16x16x32_bf16 v[68:71], v[186:189], v[218:221], v[68:71]
	v_mfma_f32_16x16x32_bf16 v[124:127], v[182:185], v[198:201], v[124:127]
	v_mfma_f32_16x16x32_bf16 v[116:119], v[190:193], v[198:201], v[116:119]
	v_mfma_f32_16x16x32_bf16 v[108:111], v[182:185], v[206:209], v[108:111]
	v_mfma_f32_16x16x32_bf16 v[100:103], v[190:193], v[206:209], v[100:103]
	v_mfma_f32_16x16x32_bf16 v[92:95], v[182:185], v[214:217], v[92:95]
	v_mfma_f32_16x16x32_bf16 v[84:87], v[190:193], v[214:217], v[84:87]
	v_mfma_f32_16x16x32_bf16 v[76:79], v[182:185], v[222:225], v[76:79]
	v_mfma_f32_16x16x32_bf16 v[68:71], v[190:193], v[222:225], v[68:71]
	s_setprio 0
	s_barrier
; #define PG8_STAGE(bufoff, gbase, voff) do { _Pragma("unroll") for (int _i = 0; _i < 2; ++_i) \
;         __builtin_amdgcn_global_load_lds((const unsigned*)((const char*)(gbase) + (voff)[_i]), (PG8_LAS unsigned*)(lds + (bufoff) + ldsw + _i * 8192), 16, 0, 0); } while (0)
; #define PG8_LDA(dst, b, h) do { _Pragma("unroll") for (int m = 0; m < 4; ++m) _Pragma("unroll") for (int k = 0; k < 2; ++k) dst[m][k] = *(const PG8_LAS bf16x8*)(lds + PG8_SA(b, h) + aoff + m * 2048 + k * 1024); } while (0)
; #define PG8_MMA(ai, bj, At, Bt) do { __builtin_amdgcn_s_setprio(1); _Pragma("unroll") for (int m = 0; m < 4; ++m) _Pragma("unroll") for (int n = 0; n < 2; ++n) _Pragma("unroll") for (int k = 0; k < 2; ++k) \
;         acc[ai][bj][m][n] = __builtin_amdgcn_mfma_f32_16x16x32_bf16(Bt[n][k], At[m][k], acc[ai][bj][m][n], 0, 0, 0); __builtin_amdgcn_s_setprio(0); } while (0)
; #define PG8_WAIT_V(n) asm volatile("s_waitcnt vmcnt(" #n ")" ::: "memory")
; #define PG8_WAIT_L(n) asm volatile("s_waitcnt lgkmcnt(" #n ")" ::: "memory")
; #define PG8_BAR __builtin_amdgcn_s_barrier()
; #define PG8_SCHED __builtin_amdgcn_sched_barrier(0)
; template <class Epi, class Sched, bool ALIGN_EPI = false, bool SP2 = false>
; __device__ __forceinline__ void gemm_phase(PG8_LAS unsigned char* lds, const Gemm g, const Sched& S, const Epi& E, const int tid) {
;     ...
;         for (int t = 0; t < nt; t += 2) {
;     ...
;             PG8_WAIT_V(8); PG8_WAIT_L(0); PG8_BAR; PG8_MMA(0, 0, At, B0); PG8_MMA(0, 1, At, B1); PG8_BAR; PG8_SCHED;
;             PG8_LDA(At, 1, 1); PG8_STAGE(PG8_SB(1, 0), b3, voffB); PG8_STAGE(PG8_SB(1, 1), b3 + hstep, voffB); PG8_STAGE(PG8_SA(1, 0), a3, voffA);
;             PG8_WAIT_V(8); PG8_WAIT_L(0); PG8_BAR; PG8_MMA(1, 0, At, B0); PG8_MMA(1, 1, At, B1); PG8_BAR; PG8_SCHED;
	s_add_i32 s22, s52, s37
	v_lshl_add_u64 v[226:227], v[226:227], 0, s[0:1]
	s_mov_b32 m0, s22
	ds_read_b128 v[194:197], v153 offset:49152
	ds_read_b128 v[198:201], v153 offset:50176
	ds_read_b128 v[202:205], v153 offset:51200
	ds_read_b128 v[206:209], v153 offset:52224
	ds_read_b128 v[210:213], v153 offset:53248
	ds_read_b128 v[214:217], v153 offset:54272
	ds_read_b128 v[218:221], v153 offset:55296
	ds_read_b128 v[222:225], v153 offset:56320
	global_load_lds_dwordx4 v[226:227], off
	s_add_i32 m0, s22, 0x2000
	s_add_u32 s20, s20, 0x40080
	v_lshl_add_u64 v[226:227], v[238:239], 0, s[0:1]
	s_addc_u32 s21, s21, 0
	s_add_i32 s22, s53, s37
	global_load_lds_dwordx4 v[226:227], off
	v_lshl_add_u64 v[226:227], s[20:21], 0, v[134:135]
	s_mov_b32 m0, s22
	s_nop 0
	global_load_lds_dwordx4 v[226:227], off
	v_lshl_add_u64 v[226:227], s[20:21], 0, v[0:1]
	s_add_i32 m0, s22, 0x2000
	s_nop 0
	global_load_lds_dwordx4 v[226:227], off
	v_lshl_add_u64 v[226:227], v[240:241], 0, s[0:1]
	s_mov_b32 m0, s42
	s_nop 0
	global_load_lds_dwordx4 v[226:227], off
	v_lshl_add_u64 v[226:227], v[242:243], 0, s[0:1]
	s_mov_b32 m0, s43
	s_nop 0
	global_load_lds_dwordx4 v[226:227], off
	s_waitcnt vmcnt(8)
	s_waitcnt lgkmcnt(0)
	s_barrier
	s_setprio 1
	s_waitcnt lgkmcnt(0)
	v_mfma_f32_16x16x32_bf16 v[64:67], v[142:145], v[194:197], v[64:67]
	v_mfma_f32_16x16x32_bf16 v[56:59], v[170:173], v[194:197], v[56:59]
	v_mfma_f32_16x16x32_bf16 v[48:51], v[142:145], v[202:205], v[48:51]
	v_mfma_f32_16x16x32_bf16 v[40:43], v[170:173], v[202:205], v[40:43]
	v_mfma_f32_16x16x32_bf16 v[32:35], v[142:145], v[210:213], v[32:35]
	v_mfma_f32_16x16x32_bf16 v[24:27], v[170:173], v[210:213], v[24:27]
	v_mfma_f32_16x16x32_bf16 v[16:19], v[142:145], v[218:221], v[16:19]
	v_mfma_f32_16x16x32_bf16 v[8:11], v[170:173], v[218:221], v[8:11]
	v_mfma_f32_16x16x32_bf16 v[64:67], v[166:169], v[198:201], v[64:67]
	v_mfma_f32_16x16x32_bf16 v[56:59], v[174:177], v[198:201], v[56:59]
	v_mfma_f32_16x16x32_bf16 v[48:51], v[166:169], v[206:209], v[48:51]
	v_mfma_f32_16x16x32_bf16 v[40:43], v[174:177], v[206:209], v[40:43]
	v_mfma_f32_16x16x32_bf16 v[32:35], v[166:169], v[214:217], v[32:35]
	v_mfma_f32_16x16x32_bf16 v[24:27], v[174:177], v[214:217], v[24:27]
	v_mfma_f32_16x16x32_bf16 v[16:19], v[166:169], v[222:225], v[16:19]
	v_mfma_f32_16x16x32_bf16 v[8:11], v[174:177], v[222:225], v[8:11]
	s_setprio 0
	s_setprio 1
	v_mfma_f32_16x16x32_bf16 v[60:63], v[178:181], v[194:197], v[60:63]
	v_mfma_f32_16x16x32_bf16 v[52:55], v[186:189], v[194:197], v[52:55]
	v_mfma_f32_16x16x32_bf16 v[44:47], v[178:181], v[202:205], v[44:47]
	v_mfma_f32_16x16x32_bf16 v[36:39], v[186:189], v[202:205], v[36:39]
	v_mfma_f32_16x16x32_bf16 v[28:31], v[178:181], v[210:213], v[28:31]
	v_mfma_f32_16x16x32_bf16 v[20:23], v[186:189], v[210:213], v[20:23]
	v_mfma_f32_16x16x32_bf16 v[12:15], v[178:181], v[218:221], v[12:15]
	v_mfma_f32_16x16x32_bf16 v[4:7], v[186:189], v[218:221], v[4:7]
	v_mfma_f32_16x16x32_bf16 v[60:63], v[182:185], v[198:201], v[60:63]
	v_mfma_f32_16x16x32_bf16 v[52:55], v[190:193], v[198:201], v[52:55]
	v_mfma_f32_16x16x32_bf16 v[44:47], v[182:185], v[206:209], v[44:47]
	v_mfma_f32_16x16x32_bf16 v[36:39], v[190:193], v[206:209], v[36:39]
	v_mfma_f32_16x16x32_bf16 v[28:31], v[182:185], v[214:217], v[28:31]
	v_mfma_f32_16x16x32_bf16 v[20:23], v[190:193], v[214:217], v[20:23]
	v_mfma_f32_16x16x32_bf16 v[12:15], v[182:185], v[222:225], v[12:15]
	v_mfma_f32_16x16x32_bf16 v[4:7], v[190:193], v[222:225], v[4:7]
	s_setprio 0
	s_add_i32 s51, s51, 2
	s_add_u32 s18, s18, 0x100
	s_addc_u32 s19, s19, 0
	s_add_u32 s49, s49, 0x100
	s_addc_u32 s50, s50, 0
	s_cmp_gt_u32 s51, 13
	s_barrier
	s_cbranch_scc0 .LBB0_522
	s_and_b64 vcc, exec, s[8:9]
	s_cbranch_vccz .LBB0_525
	s_barrier

; #define PG8_STAGE(bufoff, gbase, voff) do { _Pragma("unroll") for (int _i = 0; _i < 2; ++_i) \
;         __builtin_amdgcn_global_load_lds((const unsigned*)((const char*)(gbase) + (voff)[_i]), (PG8_LAS unsigned*)(lds + (bufoff) + ldsw + _i * 8192), 16, 0, 0); } while (0)
; #define PG8_LDA(dst, b, h) do { _Pragma("unroll") for (int m = 0; m < 4; ++m) _Pragma("unroll") for (int k = 0; k < 2; ++k) dst[m][k] = *(const PG8_LAS bf16x8*)(lds + PG8_SA(b, h) + aoff + m * 2048 + k * 1024); } while (0)
; #define PG8_LDB(dst, b, h) do { _Pragma("unroll") for (int n = 0; n < 2; ++n) _Pragma("unroll") for (int k = 0; k < 2; ++k) dst[n][k] = *(const PG8_LAS bf16x8*)(lds + PG8_SB(b, h) + boff + n * 2048 + k * 1024); } while (0)
; #define PG8_MMA(ai, bj, At, Bt) do { __builtin_amdgcn_s_setprio(1); _Pragma("unroll") for (int m = 0; m < 4; ++m) _Pragma("unroll") for (int n = 0; n < 2; ++n) _Pragma("unroll") for (int k = 0; k < 2; ++k) \
;         acc[ai][bj][m][n] = __builtin_amdgcn_mfma_f32_16x16x32_bf16(Bt[n][k], At[m][k], acc[ai][bj][m][n], 0, 0, 0); __builtin_amdgcn_s_setprio(0); } while (0)
; #define PG8_WAIT_V(n) asm volatile("s_waitcnt vmcnt(" #n ")" ::: "memory")
; #define PG8_BAR __builtin_amdgcn_s_barrier()
; template <class Epi, class Sched, bool ALIGN_EPI = false, bool SP2 = false>
; __device__ __forceinline__ void gemm_phase(PG8_LAS unsigned char* lds, const Gemm g, const Sched& S, const Epi& E, const int tid) {
;     ...
;         for (int t = 0; t < nt; t += 2) {
;             const bool last = (t == nt - 2);
;             const char* a1 = cA + (size_t)(t + 1) * kstep;
;             const char* a2 = last ? nA : cA + (size_t)(t + 2) * kstep; const char* b2 = last ? nB : cB + (size_t)(t + 2) * kstep;
;             const char* a3 = a2 + kstep; const char* b3 = b2 + kstep;
;             if (last && has_next) S.a_ready(nxt);
;             if constexpr (SP2) {
;             PG8_LDB(B0, 0, 0); PG8_LDB(B1, 0, 1); PG8_SCHED; PG8_LDA(At, 0, 0); PG8_STAGE(PG8_SA(1, 1), a1 + hstep, voffA);
;             PG8_WAIT_V(8); PG8_WAIT_L(0); PG8_BAR; PG8_MMA(0, 0, At, B0); PG8_MMA(0, 1, At, B1); PG8_BAR; PG8_SCHED;
;             PG8_LDA(At, 0, 1); PG8_STAGE(PG8_SB(0, 0), b2, voffB); PG8_STAGE(PG8_SB(0, 1), b2 + hstep, voffB); PG8_STAGE(PG8_SA(0, 0), a2, voffA);
;             PG8_WAIT_V(8); PG8_WAIT_L(0); PG8_BAR; PG8_MMA(1, 0, At, B0); PG8_MMA(1, 1, At, B1); PG8_BAR; PG8_SCHED;
.LBB0_842:
	s_add_i32 s50, 0, 0x10000
	v_add_u32_e32 v148, s50, v146
	s_add_i32 s52, 0, 0x14000
	ds_read_b128 v[142:145], v148
	ds_read_b128 v[166:169], v148 offset:1024
	ds_read_b128 v[170:173], v148 offset:2048
	ds_read_b128 v[174:177], v148 offset:3072
	v_add_u32_e32 v148, s52, v146
	ds_read_b128 v[178:181], v148
	ds_read_b128 v[182:185], v148 offset:1024
	ds_read_b128 v[186:189], v148 offset:2048
	ds_read_b128 v[190:193], v148 offset:3072
	s_add_u32 s24, s22, 0xfffc0080
	s_addc_u32 s25, s23, -1
	s_cmp_eq_u32 s49, 12
	s_cselect_b32 s27, s13, s25
	s_cselect_b32 s26, s19, s24
	s_cselect_b32 s25, s11, s48
	s_cselect_b32 s24, s46, s47
	v_lshl_add_u64 v[226:227], s[22:23], 0, v[138:139]
	s_add_i32 m0, s21, 0xc000
	ds_read_b128 v[194:197], v153
	ds_read_b128 v[198:201], v153 offset:1024
	ds_read_b128 v[202:205], v153 offset:2048
	ds_read_b128 v[206:209], v153 offset:3072
	ds_read_b128 v[210:213], v153 offset:4096
	ds_read_b128 v[214:217], v153 offset:5120
	ds_read_b128 v[218:221], v153 offset:6144
	ds_read_b128 v[222:225], v153 offset:7168
	global_load_lds_dwordx4 v[226:227], off
	v_lshl_add_u64 v[226:227], s[22:23], 0, v[140:141]
	s_add_i32 m0, s21, 0xe000
	s_nop 0
	global_load_lds_dwordx4 v[226:227], off
	s_waitcnt vmcnt(8)
	s_waitcnt lgkmcnt(0)
	s_barrier
	s_setprio 1
	s_waitcnt lgkmcnt(0)
	v_mfma_f32_16x16x32_bf16 v[128:131], v[142:145], v[194:197], v[128:131]
	v_mfma_f32_16x16x32_bf16 v[124:127], v[170:173], v[194:197], v[124:127]
	v_mfma_f32_16x16x32_bf16 v[112:115], v[142:145], v[202:205], v[112:115]
	v_mfma_f32_16x16x32_bf16 v[108:111], v[170:173], v[202:205], v[108:111]
	v_mfma_f32_16x16x32_bf16 v[96:99], v[142:145], v[210:213], v[96:99]
	v_mfma_f32_16x16x32_bf16 v[92:95], v[170:173], v[210:213], v[92:95]
	v_mfma_f32_16x16x32_bf16 v[80:83], v[142:145], v[218:221], v[80:83]
	v_mfma_f32_16x16x32_bf16 v[76:79], v[170:173], v[218:221], v[76:79]
	v_mfma_f32_16x16x32_bf16 v[128:131], v[166:169], v[198:201], v[128:131]
	v_mfma_f32_16x16x32_bf16 v[124:127], v[174:177], v[198:201], v[124:127]
	v_mfma_f32_16x16x32_bf16 v[112:115], v[166:169], v[206:209], v[112:115]
	v_mfma_f32_16x16x32_bf16 v[108:111], v[174:177], v[206:209], v[108:111]
	v_mfma_f32_16x16x32_bf16 v[96:99], v[166:169], v[214:217], v[96:99]
	v_mfma_f32_16x16x32_bf16 v[92:95], v[174:177], v[214:217], v[92:95]
	v_mfma_f32_16x16x32_bf16 v[80:83], v[166:169], v[222:225], v[80:83]
	v_mfma_f32_16x16x32_bf16 v[76:79], v[174:177], v[222:225], v[76:79]
	s_setprio 0
	s_setprio 1
	v_mfma_f32_16x16x32_bf16 v[120:123], v[178:181], v[194:197], v[120:123]
	v_mfma_f32_16x16x32_bf16 v[116:119], v[186:189], v[194:197], v[116:119]
	v_mfma_f32_16x16x32_bf16 v[104:107], v[178:181], v[202:205], v[104:107]
	v_mfma_f32_16x16x32_bf16 v[100:103], v[186:189], v[202:205], v[100:103]
	v_mfma_f32_16x16x32_bf16 v[88:91], v[178:181], v[210:213], v[88:91]
	v_mfma_f32_16x16x32_bf16 v[84:87], v[186:189], v[210:213], v[84:87]
	v_mfma_f32_16x16x32_bf16 v[72:75], v[178:181], v[218:221], v[72:75]
	v_mfma_f32_16x16x32_bf16 v[68:71], v[186:189], v[218:221], v[68:71]
	v_mfma_f32_16x16x32_bf16 v[120:123], v[182:185], v[198:201], v[120:123]
	v_mfma_f32_16x16x32_bf16 v[116:119], v[190:193], v[198:201], v[116:119]
	v_mfma_f32_16x16x32_bf16 v[104:107], v[182:185], v[206:209], v[104:107]
	v_mfma_f32_16x16x32_bf16 v[100:103], v[190:193], v[206:209], v[100:103]
	v_mfma_f32_16x16x32_bf16 v[88:91], v[182:185], v[214:217], v[88:91]
	v_mfma_f32_16x16x32_bf16 v[84:87], v[190:193], v[214:217], v[84:87]
	v_mfma_f32_16x16x32_bf16 v[72:75], v[182:185], v[222:225], v[72:75]
	v_mfma_f32_16x16x32_bf16 v[68:71], v[190:193], v[222:225], v[68:71]
	s_setprio 0
	s_barrier
	s_add_i32 s50, s50, s37
	v_lshl_add_u64 v[226:227], s[24:25], 0, v[132:133]
	s_mov_b32 m0, s50
	ds_read_b128 v[194:197], v153 offset:16384
	ds_read_b128 v[198:201], v153 offset:17408
	ds_read_b128 v[202:205], v153 offset:18432
	ds_read_b128 v[206:209], v153 offset:19456
	ds_read_b128 v[210:213], v153 offset:20480
	ds_read_b128 v[214:217], v153 offset:21504
	ds_read_b128 v[218:221], v153 offset:22528
	ds_read_b128 v[222:225], v153 offset:23552
	global_load_lds_dwordx4 v[226:227], off
	s_add_i32 m0, s50, 0x2000
	s_add_u32 s50, s24, 0x40000
	v_lshl_add_u64 v[238:239], s[24:25], 0, v[136:137]
	s_addc_u32 s51, s25, 0
	s_add_i32 s52, s52, s37
	global_load_lds_dwordx4 v[238:239], off
	v_lshl_add_u64 v[240:241], s[50:51], 0, v[132:133]
	s_mov_b32 m0, s52
	v_lshl_add_u64 v[242:243], s[26:27], 0, v[134:135]
	global_load_lds_dwordx4 v[240:241], off
	v_lshl_add_u64 v[240:241], s[50:51], 0, v[136:137]
	s_add_i32 m0, s52, 0x2000
	s_nop 0
	global_load_lds_dwordx4 v[240:241], off
	v_lshl_add_u64 v[240:241], s[26:27], 0, v[0:1]
	s_mov_b32 m0, s21
	s_nop 0
	global_load_lds_dwordx4 v[240:241], off
	s_mov_b32 m0, s40
	s_nop 0
	global_load_lds_dwordx4 v[242:243], off
	s_waitcnt vmcnt(8)
	s_waitcnt lgkmcnt(0)
	s_barrier
; #define PG8_STAGE(bufoff, gbase, voff) do { _Pragma("unroll") for (int _i = 0; _i < 2; ++_i) \
;         __builtin_amdgcn_global_load_lds((const unsigned*)((const char*)(gbase) + (voff)[_i]), (PG8_LAS unsigned*)(lds + (bufoff) + ldsw + _i * 8192), 16, 0, 0); } while (0)
; #define PG8_LDA(dst, b, h) do { _Pragma("unroll") for (int m = 0; m < 4; ++m) _Pragma("unroll") for (int k = 0; k < 2; ++k) dst[m][k] = *(const PG8_LAS bf16x8*)(lds + PG8_SA(b, h) + aoff + m * 2048 + k * 1024); } while (0)
; #define PG8_LDB(dst, b, h) do { _Pragma("unroll") for (int n = 0; n < 2; ++n) _Pragma("unroll") for (int k = 0; k < 2; ++k) dst[n][k] = *(const PG8_LAS bf16x8*)(lds + PG8_SB(b, h) + boff + n * 2048 + k * 1024); } while (0)
; #define PG8_MMA(ai, bj, At, Bt) do { __builtin_amdgcn_s_setprio(1); _Pragma("unroll") for (int m = 0; m < 4; ++m) _Pragma("unroll") for (int n = 0; n < 2; ++n) _Pragma("unroll") for (int k = 0; k < 2; ++k) \
;         acc[ai][bj][m][n] = __builtin_amdgcn_mfma_f32_16x16x32_bf16(Bt[n][k], At[m][k], acc[ai][bj][m][n], 0, 0, 0); __builtin_amdgcn_s_setprio(0); } while (0)
; #define PG8_WAIT_V(n) asm volatile("s_waitcnt vmcnt(" #n ")" ::: "memory")
; #define PG8_WAIT_L(n) asm volatile("s_waitcnt lgkmcnt(" #n ")" ::: "memory")
; #define PG8_BAR __builtin_amdgcn_s_barrier()
; #define PG8_SCHED __builtin_amdgcn_sched_barrier(0)
; template <class Epi, class Sched, bool ALIGN_EPI = false, bool SP2 = false>
; __device__ __forceinline__ void gemm_phase(PG8_LAS unsigned char* lds, const Gemm g, const Sched& S, const Epi& E, const int tid) {
;     ...
;             PG8_WAIT_V(8); PG8_WAIT_L(0); PG8_BAR; PG8_MMA(1, 0, At, B0); PG8_MMA(1, 1, At, B1); PG8_BAR; PG8_SCHED;
;             PG8_LDB(B0, 1, 0); PG8_LDB(B1, 1, 1); PG8_SCHED; PG8_LDA(At, 1, 0); PG8_STAGE(PG8_SA(0, 1), a2 + hstep, voffA);
;             PG8_WAIT_V(8); PG8_WAIT_L(0); PG8_BAR; PG8_MMA(0, 0, At, B0); PG8_MMA(0, 1, At, B1); PG8_BAR; PG8_SCHED;
	s_setprio 1
	s_waitcnt lgkmcnt(0)
	v_mfma_f32_16x16x32_bf16 v[64:67], v[142:145], v[194:197], v[64:67]
	v_mfma_f32_16x16x32_bf16 v[60:63], v[170:173], v[194:197], v[60:63]
	v_mfma_f32_16x16x32_bf16 v[48:51], v[142:145], v[202:205], v[48:51]
	v_mfma_f32_16x16x32_bf16 v[44:47], v[170:173], v[202:205], v[44:47]
	v_mfma_f32_16x16x32_bf16 v[32:35], v[142:145], v[210:213], v[32:35]
	v_mfma_f32_16x16x32_bf16 v[28:31], v[170:173], v[210:213], v[28:31]
	v_mfma_f32_16x16x32_bf16 v[16:19], v[142:145], v[218:221], v[16:19]
	v_mfma_f32_16x16x32_bf16 v[12:15], v[170:173], v[218:221], v[12:15]
	v_mfma_f32_16x16x32_bf16 v[64:67], v[166:169], v[198:201], v[64:67]
	v_mfma_f32_16x16x32_bf16 v[60:63], v[174:177], v[198:201], v[60:63]
	v_mfma_f32_16x16x32_bf16 v[48:51], v[166:169], v[206:209], v[48:51]
	v_mfma_f32_16x16x32_bf16 v[44:47], v[174:177], v[206:209], v[44:47]
	v_mfma_f32_16x16x32_bf16 v[32:35], v[166:169], v[214:217], v[32:35]
	v_mfma_f32_16x16x32_bf16 v[28:31], v[174:177], v[214:217], v[28:31]
	v_mfma_f32_16x16x32_bf16 v[16:19], v[166:169], v[222:225], v[16:19]
	v_mfma_f32_16x16x32_bf16 v[12:15], v[174:177], v[222:225], v[12:15]
	s_setprio 0
	s_setprio 1
	v_mfma_f32_16x16x32_bf16 v[56:59], v[178:181], v[194:197], v[56:59]
	v_mfma_f32_16x16x32_bf16 v[52:55], v[186:189], v[194:197], v[52:55]
	v_mfma_f32_16x16x32_bf16 v[40:43], v[178:181], v[202:205], v[40:43]
	v_mfma_f32_16x16x32_bf16 v[36:39], v[186:189], v[202:205], v[36:39]
	v_mfma_f32_16x16x32_bf16 v[24:27], v[178:181], v[210:213], v[24:27]
	v_mfma_f32_16x16x32_bf16 v[20:23], v[186:189], v[210:213], v[20:23]
	v_mfma_f32_16x16x32_bf16 v[8:11], v[178:181], v[218:221], v[8:11]
	v_mfma_f32_16x16x32_bf16 v[4:7], v[186:189], v[218:221], v[4:7]
	v_mfma_f32_16x16x32_bf16 v[56:59], v[182:185], v[198:201], v[56:59]
	v_mfma_f32_16x16x32_bf16 v[52:55], v[190:193], v[198:201], v[52:55]
	v_mfma_f32_16x16x32_bf16 v[40:43], v[182:185], v[206:209], v[40:43]
	v_mfma_f32_16x16x32_bf16 v[36:39], v[190:193], v[206:209], v[36:39]
	v_mfma_f32_16x16x32_bf16 v[24:27], v[182:185], v[214:217], v[24:27]
	v_mfma_f32_16x16x32_bf16 v[20:23], v[190:193], v[214:217], v[20:23]
	v_mfma_f32_16x16x32_bf16 v[8:11], v[182:185], v[222:225], v[8:11]
	v_mfma_f32_16x16x32_bf16 v[4:7], v[190:193], v[222:225], v[4:7]
	s_setprio 0
	s_barrier
	s_add_i32 s50, 0, 0x18000
	v_add_u32_e32 v148, s50, v146
	s_add_i32 s51, 0, 0x1c000
	ds_read_b128 v[142:145], v148
	ds_read_b128 v[166:169], v148 offset:1024
	ds_read_b128 v[170:173], v148 offset:2048
	ds_read_b128 v[174:177], v148 offset:3072
	v_add_u32_e32 v148, s51, v146
	ds_read_b128 v[178:181], v148
	ds_read_b128 v[182:185], v148 offset:1024
	ds_read_b128 v[186:189], v148 offset:2048
	ds_read_b128 v[190:193], v148 offset:3072
	s_add_u32 s26, s26, 0x40000
	s_addc_u32 s27, s27, 0
	s_mov_b32 m0, s41
	v_lshl_add_u64 v[244:245], s[26:27], 0, v[0:1]
	ds_read_b128 v[194:197], v153 offset:32768
	ds_read_b128 v[198:201], v153 offset:33792
	ds_read_b128 v[202:205], v153 offset:34816
	ds_read_b128 v[206:209], v153 offset:35840
	ds_read_b128 v[210:213], v153 offset:36864
	ds_read_b128 v[214:217], v153 offset:37888
	ds_read_b128 v[218:221], v153 offset:38912
	ds_read_b128 v[222:225], v153 offset:39936
	global_load_lds_dwordx4 v[244:245], off
	v_lshl_add_u64 v[244:245], s[26:27], 0, v[134:135]
	s_mov_b32 m0, s42
	s_nop 0
	global_load_lds_dwordx4 v[244:245], off
	s_waitcnt vmcnt(8)
	s_waitcnt lgkmcnt(0)
	s_barrier
	s_setprio 1
	s_waitcnt lgkmcnt(0)
	v_mfma_f32_16x16x32_bf16 v[128:131], v[142:145], v[194:197], v[128:131]
	v_mfma_f32_16x16x32_bf16 v[124:127], v[170:173], v[194:197], v[124:127]
	v_mfma_f32_16x16x32_bf16 v[112:115], v[142:145], v[202:205], v[112:115]
	v_mfma_f32_16x16x32_bf16 v[108:111], v[170:173], v[202:205], v[108:111]
	v_mfma_f32_16x16x32_bf16 v[96:99], v[142:145], v[210:213], v[96:99]
	v_mfma_f32_16x16x32_bf16 v[92:95], v[170:173], v[210:213], v[92:95]
	v_mfma_f32_16x16x32_bf16 v[80:83], v[142:145], v[218:221], v[80:83]
	v_mfma_f32_16x16x32_bf16 v[76:79], v[170:173], v[218:221], v[76:79]
	v_mfma_f32_16x16x32_bf16 v[128:131], v[166:169], v[198:201], v[128:131]
	v_mfma_f32_16x16x32_bf16 v[124:127], v[174:177], v[198:201], v[124:127]
	v_mfma_f32_16x16x32_bf16 v[112:115], v[166:169], v[206:209], v[112:115]
	v_mfma_f32_16x16x32_bf16 v[108:111], v[174:177], v[206:209], v[108:111]
	v_mfma_f32_16x16x32_bf16 v[96:99], v[166:169], v[214:217], v[96:99]
	v_mfma_f32_16x16x32_bf16 v[92:95], v[174:177], v[214:217], v[92:95]
	v_mfma_f32_16x16x32_bf16 v[80:83], v[166:169], v[222:225], v[80:83]
	v_mfma_f32_16x16x32_bf16 v[76:79], v[174:177], v[222:225], v[76:79]
	s_setprio 0
	s_setprio 1
	v_mfma_f32_16x16x32_bf16 v[120:123], v[178:181], v[194:197], v[120:123]
	v_mfma_f32_16x16x32_bf16 v[116:119], v[186:189], v[194:197], v[116:119]
	v_mfma_f32_16x16x32_bf16 v[104:107], v[178:181], v[202:205], v[104:107]
	v_mfma_f32_16x16x32_bf16 v[100:103], v[186:189], v[202:205], v[100:103]
	v_mfma_f32_16x16x32_bf16 v[88:91], v[178:181], v[210:213], v[88:91]
	v_mfma_f32_16x16x32_bf16 v[84:87], v[186:189], v[210:213], v[84:87]
	v_mfma_f32_16x16x32_bf16 v[72:75], v[178:181], v[218:221], v[72:75]
	v_mfma_f32_16x16x32_bf16 v[68:71], v[186:189], v[218:221], v[68:71]
	v_mfma_f32_16x16x32_bf16 v[120:123], v[182:185], v[198:201], v[120:123]
	v_mfma_f32_16x16x32_bf16 v[116:119], v[190:193], v[198:201], v[116:119]
	v_mfma_f32_16x16x32_bf16 v[104:107], v[182:185], v[206:209], v[104:107]
	v_mfma_f32_16x16x32_bf16 v[100:103], v[190:193], v[206:209], v[100:103]
	v_mfma_f32_16x16x32_bf16 v[88:91], v[182:185], v[214:217], v[88:91]
	v_mfma_f32_16x16x32_bf16 v[84:87], v[190:193], v[214:217], v[84:87]
	v_mfma_f32_16x16x32_bf16 v[72:75], v[182:185], v[222:225], v[72:75]
	v_mfma_f32_16x16x32_bf16 v[68:71], v[190:193], v[222:225], v[68:71]
	s_setprio 0
	s_barrier
; #define PG8_STAGE(bufoff, gbase, voff) do { _Pragma("unroll") for (int _i = 0; _i < 2; ++_i) \
;         __builtin_amdgcn_global_load_lds((const unsigned*)((const char*)(gbase) + (voff)[_i]), (PG8_LAS unsigned*)(lds + (bufoff) + ldsw + _i * 8192), 16, 0, 0); } while (0)
; #define PG8_LDA(dst, b, h) do { _Pragma("unroll") for (int m = 0; m < 4; ++m) _Pragma("unroll") for (int k = 0; k < 2; ++k) dst[m][k] = *(const PG8_LAS bf16x8*)(lds + PG8_SA(b, h) + aoff + m * 2048 + k * 1024); } while (0)
; #define PG8_MMA(ai, bj, At, Bt) do { __builtin_amdgcn_s_setprio(1); _Pragma("unroll") for (int m = 0; m < 4; ++m) _Pragma("unroll") for (int n = 0; n < 2; ++n) _Pragma("unroll") for (int k = 0; k < 2; ++k) \
;         acc[ai][bj][m][n] = __builtin_amdgcn_mfma_f32_16x16x32_bf16(Bt[n][k], At[m][k], acc[ai][bj][m][n], 0, 0, 0); __builtin_amdgcn_s_setprio(0); } while (0)
; #define PG8_WAIT_V(n) asm volatile("s_waitcnt vmcnt(" #n ")" ::: "memory")
; #define PG8_WAIT_L(n) asm volatile("s_waitcnt lgkmcnt(" #n ")" ::: "memory")
; #define PG8_BAR __builtin_amdgcn_s_barrier()
; #define PG8_SCHED __builtin_amdgcn_sched_barrier(0)
; template <class Epi, class Sched, bool ALIGN_EPI = false, bool SP2 = false>
; __device__ __forceinline__ void gemm_phase(PG8_LAS unsigned char* lds, const Gemm g, const Sched& S, const Epi& E, const int tid) {
;     ...
;         for (int t = 0; t < nt; t += 2) {
;     ...
;             PG8_WAIT_V(8); PG8_WAIT_L(0); PG8_BAR; PG8_MMA(0, 0, At, B0); PG8_MMA(0, 1, At, B1); PG8_BAR; PG8_SCHED;
;             PG8_LDA(At, 1, 1); PG8_STAGE(PG8_SB(1, 0), b3, voffB); PG8_STAGE(PG8_SB(1, 1), b3 + hstep, voffB); PG8_STAGE(PG8_SA(1, 0), a3, voffA);
;             PG8_WAIT_V(8); PG8_WAIT_L(0); PG8_BAR; PG8_MMA(1, 0, At, B0); PG8_MMA(1, 1, At, B1); PG8_BAR; PG8_SCHED;
	s_add_i32 s26, s50, s37
	v_lshl_add_u64 v[226:227], v[226:227], 0, s[0:1]
	s_mov_b32 m0, s26
	ds_read_b128 v[194:197], v153 offset:49152
	ds_read_b128 v[198:201], v153 offset:50176
	ds_read_b128 v[202:205], v153 offset:51200
	ds_read_b128 v[206:209], v153 offset:52224
	ds_read_b128 v[210:213], v153 offset:53248
	ds_read_b128 v[214:217], v153 offset:54272
	ds_read_b128 v[218:221], v153 offset:55296
	ds_read_b128 v[222:225], v153 offset:56320
	global_load_lds_dwordx4 v[226:227], off
	s_add_i32 m0, s26, 0x2000
	s_add_u32 s24, s24, 0x40080
	v_lshl_add_u64 v[226:227], v[238:239], 0, s[0:1]
	s_addc_u32 s25, s25, 0
	s_add_i32 s26, s51, s37
	global_load_lds_dwordx4 v[226:227], off
	v_lshl_add_u64 v[226:227], s[24:25], 0, v[132:133]
	s_mov_b32 m0, s26
	s_nop 0
	global_load_lds_dwordx4 v[226:227], off
	v_lshl_add_u64 v[226:227], s[24:25], 0, v[136:137]
	s_add_i32 m0, s26, 0x2000
	s_nop 0
	global_load_lds_dwordx4 v[226:227], off
	v_lshl_add_u64 v[226:227], v[240:241], 0, s[0:1]
	s_mov_b32 m0, s43
	s_nop 0
	global_load_lds_dwordx4 v[226:227], off
	v_lshl_add_u64 v[226:227], v[242:243], 0, s[0:1]
	s_mov_b32 m0, s44
	s_nop 0
	global_load_lds_dwordx4 v[226:227], off
	s_waitcnt vmcnt(8)
	s_waitcnt lgkmcnt(0)
	s_barrier
	s_setprio 1
	s_waitcnt lgkmcnt(0)
	v_mfma_f32_16x16x32_bf16 v[64:67], v[142:145], v[194:197], v[64:67]
	v_mfma_f32_16x16x32_bf16 v[60:63], v[170:173], v[194:197], v[60:63]
	v_mfma_f32_16x16x32_bf16 v[48:51], v[142:145], v[202:205], v[48:51]
	v_mfma_f32_16x16x32_bf16 v[44:47], v[170:173], v[202:205], v[44:47]
	v_mfma_f32_16x16x32_bf16 v[32:35], v[142:145], v[210:213], v[32:35]
	v_mfma_f32_16x16x32_bf16 v[28:31], v[170:173], v[210:213], v[28:31]
	v_mfma_f32_16x16x32_bf16 v[16:19], v[142:145], v[218:221], v[16:19]
	v_mfma_f32_16x16x32_bf16 v[12:15], v[170:173], v[218:221], v[12:15]
	v_mfma_f32_16x16x32_bf16 v[64:67], v[166:169], v[198:201], v[64:67]
	v_mfma_f32_16x16x32_bf16 v[60:63], v[174:177], v[198:201], v[60:63]
	v_mfma_f32_16x16x32_bf16 v[48:51], v[166:169], v[206:209], v[48:51]
	v_mfma_f32_16x16x32_bf16 v[44:47], v[174:177], v[206:209], v[44:47]
	v_mfma_f32_16x16x32_bf16 v[32:35], v[166:169], v[214:217], v[32:35]
	v_mfma_f32_16x16x32_bf16 v[28:31], v[174:177], v[214:217], v[28:31]
	v_mfma_f32_16x16x32_bf16 v[16:19], v[166:169], v[222:225], v[16:19]
	v_mfma_f32_16x16x32_bf16 v[12:15], v[174:177], v[222:225], v[12:15]
	s_setprio 0
	s_setprio 1
	v_mfma_f32_16x16x32_bf16 v[56:59], v[178:181], v[194:197], v[56:59]
	v_mfma_f32_16x16x32_bf16 v[52:55], v[186:189], v[194:197], v[52:55]
	v_mfma_f32_16x16x32_bf16 v[40:43], v[178:181], v[202:205], v[40:43]
	v_mfma_f32_16x16x32_bf16 v[36:39], v[186:189], v[202:205], v[36:39]
	v_mfma_f32_16x16x32_bf16 v[24:27], v[178:181], v[210:213], v[24:27]
	v_mfma_f32_16x16x32_bf16 v[20:23], v[186:189], v[210:213], v[20:23]
	v_mfma_f32_16x16x32_bf16 v[8:11], v[178:181], v[218:221], v[8:11]
	v_mfma_f32_16x16x32_bf16 v[4:7], v[186:189], v[218:221], v[4:7]
	v_mfma_f32_16x16x32_bf16 v[56:59], v[182:185], v[198:201], v[56:59]
	v_mfma_f32_16x16x32_bf16 v[52:55], v[190:193], v[198:201], v[52:55]
	v_mfma_f32_16x16x32_bf16 v[40:43], v[182:185], v[206:209], v[40:43]
	v_mfma_f32_16x16x32_bf16 v[36:39], v[190:193], v[206:209], v[36:39]
	v_mfma_f32_16x16x32_bf16 v[24:27], v[182:185], v[214:217], v[24:27]
	v_mfma_f32_16x16x32_bf16 v[20:23], v[190:193], v[214:217], v[20:23]
	v_mfma_f32_16x16x32_bf16 v[8:11], v[182:185], v[222:225], v[8:11]
	v_mfma_f32_16x16x32_bf16 v[4:7], v[190:193], v[222:225], v[4:7]
	s_setprio 0
	s_add_i32 s49, s49, 2
	s_add_u32 s22, s22, 0x100
	s_addc_u32 s23, s23, 0
	s_add_u32 s47, s47, 0x100
	s_addc_u32 s48, s48, 0
	s_cmp_gt_u32 s49, 13
	s_barrier
	s_cbranch_scc0 .LBB0_842
	s_and_b64 vcc, exec, s[8:9]
	s_cbranch_vccz .LBB0_845
	s_barrier
